# speedup vs baseline: 1.0296x; 1.0022x over previous
.LBB0_349:
	s_or_b64 exec, exec, s[90:91]
	v_mov_b32_e32 v0, v180
	s_waitcnt lgkmcnt(0)
	s_barrier
	s_nop 0
	v_cmp_gt_i32_e32 vcc, s56, v0
	s_and_saveexec_b64 s[90:91], vcc
	s_cbranch_execz .LBB0_351
	v_ashrrev_i32_e32 v5, 31, v0
	v_add_u32_sdwa v5, v0, v5 dst_sel:DWORD dst_unused:UNUSED_PAD src0_sel:DWORD src1_sel:BYTE_3
	v_ashrrev_i32_e32 v5, 8, v5
	v_mul_i32_i24_e32 v7, 0x100, v5
	v_sub_u32_e32 v7, v0, v7
	v_ashrrev_i16_e32 v0, 15, v7
	v_lshrrev_b16_e32 v0, 12, v0
	v_add_u16_e32 v11, v7, v0
	v_ashrrev_i16_e32 v0, 4, v11
	v_and_b32_e32 v11, -16, v11
	v_mul_i32_i24_e32 v5, 0x1100, v5
	v_sub_u16_e32 v11, v7, v11
	v_lshlrev_b32_e32 v5, 3, v5
	v_lshlrev_b32_e32 v17, 3, v7
	v_ashrrev_i32_e32 v7, 4, v7
	v_add_u32_e32 v13, s57, v5
	v_lshlrev_b32_e32 v7, 3, v7
	v_add3_u32 v7, v13, v17, v7
	ds_read_b64 v[26:27], v7
	ds_read_b64 v[28:29], v7 offset:2176
	ds_read_b64 v[114:115], v7 offset:4352
	ds_read_b64 v[116:117], v7 offset:6528
	ds_read_b64 v[118:119], v7 offset:8704
	ds_read_b64 v[122:123], v7 offset:10880
	ds_read_b64 v[124:125], v7 offset:13056
	ds_read_b64 v[126:127], v7 offset:15232
	ds_read_b64 v[128:129], v7 offset:17408
	ds_read_b64 v[130:131], v7 offset:19584
	ds_read_b64 v[132:133], v7 offset:21760
	ds_read_b64 v[134:135], v7 offset:23936
	ds_read_b64 v[136:137], v7 offset:26112
	ds_read_b64 v[138:139], v7 offset:28288
	ds_read_b64 v[140:141], v7 offset:30464
	ds_read_b64 v[96:97], v7 offset:32640
	v_bfe_i32 v7, v11, 0, 16
	v_mad_i32_i24 v11, v7, s27, 0
	v_add_u32_e32 v13, 0x808, v11
	ds_read2_b64 v[108:111], v13 offset1:1
	v_add_u32_e32 v13, 0x818, v11
	s_mov_b32 s61, s34
	s_mov_b32 s35, s24
	v_bfe_i32 v0, v0, 0, 16
	s_waitcnt lgkmcnt(0)
	v_pk_mul_f32 v[82:83], v[28:29], v[108:109] op_sel:[1,1] op_sel_hi:[1,0]
	v_lshl_add_u32 v0, v0, 8, v7
	v_pk_fma_f32 v[106:107], v[28:29], v[108:109], v[82:83] op_sel_hi:[0,1,1] neg_lo:[0,0,1]
	v_pk_mul_f32 v[28:29], v[114:115], v[110:111] op_sel:[1,1] op_sel_hi:[1,0]
	v_lshlrev_b32_e32 v7, 3, v0
	v_pk_fma_f32 v[82:83], v[114:115], v[110:111], v[28:29] op_sel_hi:[0,1,1] neg_lo:[0,0,1]
	ds_read2_b64 v[108:111], v13 offset1:1
	v_add_u32_e32 v13, 0x828, v11
	v_ashrrev_i32_e32 v0, 4, v0
	v_add_u32_e32 v5, 0, v5
	s_waitcnt lgkmcnt(0)
	v_pk_mul_f32 v[114:115], v[116:117], v[108:109] op_sel:[1,1] op_sel_hi:[1,0]
	v_lshlrev_b32_e32 v0, 3, v0
	v_pk_fma_f32 v[28:29], v[116:117], v[108:109], v[114:115] op_sel_hi:[0,1,1] neg_lo:[0,0,1]
	v_pk_mul_f32 v[108:109], v[118:119], v[110:111] op_sel:[1,1] op_sel_hi:[1,0]
	v_add3_u32 v0, v5, v7, v0
	v_pk_fma_f32 v[116:117], v[118:119], v[110:111], v[108:109] op_sel_hi:[0,1,1] neg_lo:[0,0,1]
	ds_read2_b64 v[118:121], v13 offset1:1
	v_add_u32_e32 v13, 0x838, v11
	v_add_u32_e32 v5, 0x1800, v0
	v_add_u32_e32 v0, 0x1c00, v0
	s_waitcnt lgkmcnt(0)
	v_pk_mul_f32 v[108:109], v[122:123], v[118:119] op_sel:[1,1] op_sel_hi:[1,0]
	s_nop 0
	v_pk_fma_f32 v[114:115], v[122:123], v[118:119], v[108:109] op_sel_hi:[0,1,1] neg_lo:[0,0,1]
	v_pk_mul_f32 v[108:109], v[124:125], v[120:121] op_sel:[1,1] op_sel_hi:[1,0]
	s_nop 0
	v_pk_fma_f32 v[110:111], v[124:125], v[120:121], v[108:109] op_sel_hi:[0,1,1] neg_lo:[0,0,1]
	ds_read2_b64 v[118:121], v13 offset1:1
	v_add_u32_e32 v13, 0x848, v11
	s_waitcnt lgkmcnt(0)
	v_pk_mul_f32 v[122:123], v[126:127], v[118:119] op_sel:[1,1] op_sel_hi:[1,0]
	s_nop 0
	v_pk_fma_f32 v[108:109], v[126:127], v[118:119], v[122:123] op_sel_hi:[0,1,1] neg_lo:[0,0,1]
	v_pk_mul_f32 v[118:119], v[128:129], v[120:121] op_sel:[1,1] op_sel_hi:[1,0]
	s_nop 0
	v_pk_fma_f32 v[124:125], v[128:129], v[120:121], v[118:119] op_sel_hi:[0,1,1] neg_lo:[0,0,1]
	ds_read2_b64 v[126:129], v13 offset1:1
	v_add_u32_e32 v13, 0x858, v11
	s_waitcnt lgkmcnt(0)
	v_pk_mul_f32 v[118:119], v[130:131], v[126:127] op_sel:[1,1] op_sel_hi:[1,0]
	s_nop 0
	v_pk_fma_f32 v[122:123], v[130:131], v[126:127], v[118:119] op_sel_hi:[0,1,1] neg_lo:[0,0,1]
	v_pk_mul_f32 v[118:119], v[132:133], v[128:129] op_sel:[1,1] op_sel_hi:[1,0]
	s_nop 0
	v_pk_fma_f32 v[120:121], v[132:133], v[128:129], v[118:119] op_sel_hi:[0,1,1] neg_lo:[0,0,1]
	ds_read2_b64 v[126:129], v13 offset1:1
	v_add_u32_e32 v13, 0x868, v11
	s_waitcnt lgkmcnt(0)
	v_pk_mul_f32 v[130:131], v[134:135], v[126:127] op_sel:[1,1] op_sel_hi:[1,0]
	s_nop 0
	v_pk_fma_f32 v[118:119], v[134:135], v[126:127], v[130:131] op_sel_hi:[0,1,1] neg_lo:[0,0,1]
	ds_read2_b64 v[132:135], v13 offset1:1
	v_pk_mul_f32 v[126:127], v[136:137], v[128:129] op_sel:[1,1] op_sel_hi:[1,0]
	s_nop 0
	v_pk_fma_f32 v[130:131], v[136:137], v[128:129], v[126:127] op_sel_hi:[0,1,1] neg_lo:[0,0,1]
	s_waitcnt lgkmcnt(0)
	v_pk_mul_f32 v[126:127], v[138:139], v[132:133] op_sel:[1,1] op_sel_hi:[1,0]
	s_nop 0
	v_pk_fma_f32 v[128:129], v[138:139], v[132:133], v[126:127] op_sel_hi:[0,1,1] neg_lo:[0,0,1]
	v_pk_mul_f32 v[132:133], v[140:141], v[134:135] op_sel:[1,1] op_sel_hi:[1,0]
	v_pk_fma_f32 v[126:127], v[140:141], v[134:135], v[132:133] op_sel_hi:[0,1,1] neg_lo:[0,0,1]
	ds_read_b64 v[132:133], v11 offset:2168
	s_waitcnt lgkmcnt(0)
	v_pk_mul_f32 v[134:135], v[96:97], v[132:133] op_sel:[1,1] op_sel_hi:[1,0]
	s_nop 0
	v_pk_fma_f32 v[136:137], v[96:97], v[132:133], v[134:135] op_sel_hi:[0,1,1] neg_lo:[0,0,1]
	v_pk_add_f32 v[96:97], v[26:27], v[124:125]
	v_pk_add_f32 v[26:27], v[26:27], v[124:125] neg_lo:[0,1] neg_hi:[0,1]
	v_pk_add_f32 v[124:125], v[116:117], v[130:131]
	v_pk_add_f32 v[116:117], v[116:117], v[130:131] neg_lo:[0,1] neg_hi:[0,1]
	s_nop 0
	v_xor_b32_e32 v131, 0x80000000, v116
	v_mov_b32_e32 v130, v117
	v_pk_add_f32 v[116:117], v[96:97], v[124:125]
	v_pk_add_f32 v[96:97], v[96:97], v[124:125] neg_lo:[0,1] neg_hi:[0,1]
	v_pk_add_f32 v[124:125], v[106:107], v[122:123]
	v_pk_add_f32 v[106:107], v[106:107], v[122:123] neg_lo:[0,1] neg_hi:[0,1]
	v_pk_add_f32 v[122:123], v[114:115], v[128:129]
	v_pk_add_f32 v[114:115], v[114:115], v[128:129] neg_lo:[0,1] neg_hi:[0,1]
	v_pk_add_f32 v[132:133], v[26:27], v[130:131]
	v_xor_b32_e32 v129, 0x80000000, v114
	v_mov_b32_e32 v128, v115
	v_pk_add_f32 v[114:115], v[124:125], v[122:123]
	v_pk_add_f32 v[122:123], v[124:125], v[122:123] neg_lo:[0,1] neg_hi:[0,1]
	v_pk_add_f32 v[124:125], v[82:83], v[120:121]
	v_pk_add_f32 v[82:83], v[82:83], v[120:121] neg_lo:[0,1] neg_hi:[0,1]
	v_pk_add_f32 v[120:121], v[110:111], v[126:127]
	v_pk_add_f32 v[110:111], v[110:111], v[126:127] neg_lo:[0,1] neg_hi:[0,1]
	v_pk_add_f32 v[26:27], v[26:27], v[130:131] neg_lo:[0,1] neg_hi:[0,1]
	v_pk_add_f32 v[130:131], v[106:107], v[128:129]
	v_xor_b32_e32 v127, 0x80000000, v110
	v_mov_b32_e32 v126, v111
	v_pk_add_f32 v[110:111], v[124:125], v[120:121]
	v_pk_add_f32 v[120:121], v[124:125], v[120:121] neg_lo:[0,1] neg_hi:[0,1]
	v_pk_add_f32 v[124:125], v[28:29], v[118:119]
	v_pk_add_f32 v[28:29], v[28:29], v[118:119] neg_lo:[0,1] neg_hi:[0,1]
	v_pk_add_f32 v[118:119], v[108:109], v[136:137]
	v_pk_add_f32 v[108:109], v[108:109], v[136:137] neg_lo:[0,1] neg_hi:[0,1]
	v_pk_add_f32 v[106:107], v[106:107], v[128:129] neg_lo:[0,1] neg_hi:[0,1]
	v_pk_add_f32 v[128:129], v[82:83], v[126:127]
	v_pk_add_f32 v[82:83], v[82:83], v[126:127] neg_lo:[0,1] neg_hi:[0,1]
	v_xor_b32_e32 v127, 0x80000000, v108
	v_mov_b32_e32 v126, v109
	v_pk_add_f32 v[108:109], v[124:125], v[118:119]
	v_pk_add_f32 v[118:119], v[124:125], v[118:119] neg_lo:[0,1] neg_hi:[0,1]
	v_pk_mul_f32 v[124:125], v[130:131], s[24:25] op_sel_hi:[1,0]
	v_pk_add_f32 v[134:135], v[28:29], v[126:127]
	v_pk_add_f32 v[28:29], v[28:29], v[126:127] neg_lo:[0,1] neg_hi:[0,1]
	v_pk_fma_f32 v[126:127], v[130:131], s[26:27], v[124:125] op_sel:[0,0,1] op_sel_hi:[1,0,0]
	v_pk_fma_f32 v[124:125], v[130:131], s[26:27], v[124:125] op_sel:[0,0,1] op_sel_hi:[1,0,0] neg_lo:[0,0,1] neg_hi:[0,0,1]
	s_nop 0
	v_mov_b32_e32 v127, v125
	v_pk_mul_f32 v[124:125], v[122:123], s[28:29] op_sel_hi:[1,0]
	s_nop 0
	v_pk_fma_f32 v[130:131], v[122:123], s[28:29], v[124:125] op_sel:[0,0,1] op_sel_hi:[1,0,0]
	v_pk_fma_f32 v[122:123], v[122:123], s[28:29], v[124:125] op_sel_hi:[1,0,0] neg_lo:[0,0,1] neg_hi:[0,0,1]
	v_pk_mul_f32 v[124:125], v[106:107], s[26:27] op_sel_hi:[1,0]
	v_mov_b32_e32 v131, v123
	v_pk_fma_f32 v[136:137], v[106:107], s[24:25], v[124:125] op_sel:[0,0,1] op_sel_hi:[1,0,0]
	v_pk_fma_f32 v[106:107], v[106:107], s[24:25], v[124:125] op_sel:[0,0,1] op_sel_hi:[1,0,0] neg_lo:[0,0,1] neg_hi:[0,0,1]
	s_nop 0
	v_mov_b32_e32 v137, v107
	v_pk_mul_f32 v[106:107], v[128:129], s[28:29] op_sel_hi:[1,0]
	s_nop 0
	v_pk_fma_f32 v[124:125], v[128:129], s[28:29], v[106:107] op_sel:[0,0,1] op_sel_hi:[1,0,0]
	v_pk_fma_f32 v[106:107], v[128:129], s[28:29], v[106:107] op_sel_hi:[1,0,0] neg_lo:[0,0,1] neg_hi:[0,0,1]
	s_nop 0
	v_mov_b32_e32 v125, v107
	v_pk_fma_f32 v[106:107], v[120:121], 0, v[120:121] op_sel:[0,0,1] op_sel_hi:[1,0,0]
	v_pk_fma_f32 v[120:121], v[120:121], 0, v[120:121] op_sel:[0,0,1] op_sel_hi:[1,0,0] neg_lo:[0,0,1] neg_hi:[0,0,1]
	s_nop 0
	v_mov_b32_e32 v107, v121
	v_pk_mul_f32 v[120:121], v[82:83], s[30:31] op_sel_hi:[1,0]
	s_nop 0
	v_pk_fma_f32 v[128:129], v[82:83], s[30:31], v[120:121] op_sel:[0,0,1] op_sel_hi:[1,0,0] neg_lo:[0,0,1] neg_hi:[0,0,1]
	v_pk_fma_f32 v[82:83], v[82:83], s[30:31], v[120:121] op_sel_hi:[1,0,0]
	v_pk_mul_f32 v[120:121], v[134:135], s[26:27] op_sel_hi:[1,0]
	v_mov_b32_e32 v129, v83
	v_pk_fma_f32 v[138:139], v[134:135], s[24:25], v[120:121] op_sel:[0,0,1] op_sel_hi:[1,0,0]
	v_pk_fma_f32 v[120:121], v[134:135], s[24:25], v[120:121] op_sel:[0,0,1] op_sel_hi:[1,0,0] neg_lo:[0,0,1] neg_hi:[0,0,1]
	v_pk_add_f32 v[82:83], v[26:27], v[128:129]
	v_mov_b32_e32 v139, v121
	v_pk_mul_f32 v[120:121], v[118:119], s[30:31] op_sel_hi:[1,0]
	v_pk_add_f32 v[26:27], v[26:27], v[128:129] neg_lo:[0,1] neg_hi:[0,1]
	v_pk_fma_f32 v[134:135], v[118:119], s[30:31], v[120:121] op_sel:[0,0,1] op_sel_hi:[1,0,0] neg_lo:[0,0,1] neg_hi:[0,0,1]
	v_pk_fma_f32 v[118:119], v[118:119], s[30:31], v[120:121] op_sel_hi:[1,0,0]
	s_nop 0
	v_mov_b32_e32 v135, v119
	v_pk_mul_f32 v[118:119], v[28:29], s[60:61] op_sel:[1,0]
	v_pk_add_f32 v[122:123], v[130:131], v[134:135] neg_lo:[0,1] neg_hi:[0,1]
	v_pk_fma_f32 v[28:29], v[28:29], s[34:35], v[118:119] op_sel_hi:[0,1,1]
	v_pk_add_f32 v[118:119], v[116:117], v[110:111]
	v_pk_add_f32 v[110:111], v[116:117], v[110:111] neg_lo:[0,1] neg_hi:[0,1]
	v_pk_add_f32 v[116:117], v[114:115], v[108:109]
	v_pk_add_f32 v[108:109], v[114:115], v[108:109] neg_lo:[0,1] neg_hi:[0,1]
	s_nop 0
	v_xor_b32_e32 v115, 0x80000000, v108
	v_mov_b32_e32 v114, v109
	v_pk_add_f32 v[108:109], v[118:119], v[116:117]
	v_pk_add_f32 v[120:121], v[110:111], v[114:115]
	v_pk_add_f32 v[116:117], v[118:119], v[116:117] neg_lo:[0,1] neg_hi:[0,1]
	v_pk_add_f32 v[110:111], v[110:111], v[114:115] neg_lo:[0,1] neg_hi:[0,1]
	v_pk_add_f32 v[114:115], v[132:133], v[124:125]
	v_pk_add_f32 v[118:119], v[132:133], v[124:125] neg_lo:[0,1] neg_hi:[0,1]
	v_pk_add_f32 v[124:125], v[126:127], v[138:139]
	v_pk_add_f32 v[126:127], v[126:127], v[138:139] neg_lo:[0,1] neg_hi:[0,1]
	s_nop 0
	v_xor_b32_e32 v133, 0x80000000, v126
	v_mov_b32_e32 v132, v127
	v_pk_add_f32 v[126:127], v[114:115], v[124:125]
	v_pk_add_f32 v[114:115], v[114:115], v[124:125] neg_lo:[0,1] neg_hi:[0,1]
	v_pk_add_f32 v[124:125], v[96:97], v[106:107]
	v_pk_add_f32 v[96:97], v[96:97], v[106:107] neg_lo:[0,1] neg_hi:[0,1]
	v_pk_add_f32 v[106:107], v[130:131], v[134:135]
	v_xor_b32_e32 v131, 0x80000000, v122
	v_mov_b32_e32 v130, v123
	v_pk_add_f32 v[122:123], v[124:125], v[106:107]
	v_pk_add_f32 v[106:107], v[124:125], v[106:107] neg_lo:[0,1] neg_hi:[0,1]
	v_pk_add_f32 v[124:125], v[136:137], v[28:29]
	v_pk_add_f32 v[28:29], v[136:137], v[28:29] neg_lo:[0,1] neg_hi:[0,1]
	v_pk_add_f32 v[138:139], v[118:119], v[132:133]
	v_xor_b32_e32 v129, 0x80000000, v28
	v_mov_b32_e32 v128, v29
	v_pk_add_f32 v[118:119], v[118:119], v[132:133] neg_lo:[0,1] neg_hi:[0,1]
	v_pk_add_f32 v[132:133], v[96:97], v[130:131]
	v_pk_add_f32 v[96:97], v[96:97], v[130:131] neg_lo:[0,1] neg_hi:[0,1]
	v_pk_add_f32 v[130:131], v[26:27], v[128:129]
	v_pk_add_f32 v[26:27], v[26:27], v[128:129] neg_lo:[0,1] neg_hi:[0,1]
	v_pk_add_f32 v[28:29], v[82:83], v[124:125]
	v_pk_add_f32 v[82:83], v[82:83], v[124:125] neg_lo:[0,1] neg_hi:[0,1]
	ds_write2_b64 v5, v[108:109], v[126:127] offset0:16 offset1:33
	ds_write2_b64 v5, v[122:123], v[28:29] offset0:50 offset1:67
	ds_write2_b64 v5, v[120:121], v[138:139] offset0:84 offset1:101
	ds_write2_b64 v5, v[132:133], v[130:131] offset0:118 offset1:135
	ds_write2_b64 v5, v[116:117], v[114:115] offset0:152 offset1:169
	ds_write2_b64 v5, v[106:107], v[82:83] offset0:186 offset1:203
	ds_write2_b64 v5, v[110:111], v[118:119] offset0:220 offset1:237
	ds_write2_b64 v0, v[96:97], v[26:27] offset0:126 offset1:143
.LBB0_351:
	s_or_b64 exec, exec, s[90:91]
	v_mov_b32_e32 v0, v180
	s_waitcnt lgkmcnt(0)
	s_barrier
	s_nop 0
	v_cmp_gt_i32_e32 vcc, s56, v0
	s_and_saveexec_b64 s[90:91], vcc
	s_cbranch_execz .LBB0_353
	v_ashrrev_i32_e32 v5, 31, v0
	v_add_u32_sdwa v5, v0, v5 dst_sel:DWORD dst_unused:UNUSED_PAD src0_sel:DWORD src1_sel:BYTE_3
	v_ashrrev_i32_e32 v5, 8, v5
	v_mul_i32_i24_e32 v7, 0x100, v5
	v_sub_u32_e32 v0, v0, v7
	v_mul_i32_i24_e32 v5, 0x1100, v5
	v_lshlrev_b32_e32 v7, 3, v0
	v_ashrrev_i32_e32 v0, 4, v0
	v_lshlrev_b32_e32 v5, 3, v5
	v_lshlrev_b32_e32 v0, 3, v0
	v_add_u32_e32 v11, 0, v7
	v_add3_u32 v13, v11, v5, v0
	ds_read_b64 v[26:27], v13 offset:6272
	ds_read_b64 v[28:29], v13 offset:8448
	ds_read_b64 v[82:83], v13 offset:10624
	ds_read_b64 v[96:97], v13 offset:12800
	ds_read_b64 v[106:107], v13 offset:14976
	ds_read_b64 v[108:109], v13 offset:17152
	ds_read_b64 v[110:111], v13 offset:19328
	ds_read_b64 v[114:115], v13 offset:21504
	ds_read_b64 v[116:117], v13 offset:34560
	ds_read_b64 v[118:119], v13 offset:36736
	ds_read_b64 v[120:121], v13 offset:38912
	ds_read_b64 v[122:123], v11
	ds_read_b64 v[124:125], v13 offset:23680
	ds_read_b64 v[126:127], v13 offset:25856
	ds_read_b64 v[128:129], v13 offset:28032
	ds_read_b64 v[130:131], v13 offset:30208
	ds_read_b64 v[132:133], v13 offset:32384
	s_waitcnt lgkmcnt(5)
	v_pk_mul_f32 v[134:135], v[28:29], v[122:123] op_sel:[1,1] op_sel_hi:[1,0]
	s_mov_b32 s61, s34
	v_pk_fma_f32 v[136:137], v[28:29], v[122:123], v[134:135] op_sel_hi:[0,1,1] neg_lo:[0,0,1]
	v_pk_mul_f32 v[28:29], v[122:123], v[122:123] op_sel:[1,1] op_sel_hi:[1,0]
	s_mov_b32 s35, s24
	v_pk_fma_f32 v[134:135], v[122:123], v[122:123], v[28:29] op_sel_hi:[1,0,1] neg_lo:[0,0,1] neg_hi:[0,0,1]
	v_pk_fma_f32 v[28:29], v[122:123], v[122:123], v[28:29] op_sel_hi:[1,0,1]
	v_mov_b32_e32 v138, v134
	v_mov_b32_e32 v139, v29
	v_pk_mul_f32 v[28:29], v[82:83], v[28:29] op_sel:[1,1] op_sel_hi:[0,1]
	v_pk_fma_f32 v[140:141], v[82:83], v[134:135], v[28:29] neg_lo:[0,0,1] neg_hi:[0,0,1]
	v_pk_fma_f32 v[28:29], v[82:83], v[134:135], v[28:29] op_sel_hi:[1,0,1]
	v_pk_mul_f32 v[82:83], v[122:123], v[138:139] op_sel:[1,0] op_sel_hi:[0,1]
	v_mov_b32_e32 v141, v29
	v_pk_mul_f32 v[28:29], v[122:123], v[138:139]
	v_pk_add_f32 v[82:83], v[82:83], v[82:83] op_sel:[0,1] op_sel_hi:[0,1]
	v_pk_mul_f32 v[134:135], v[96:97], v[82:83]
	v_pk_add_f32 v[28:29], v[28:29], v[28:29] op_sel:[0,1] op_sel_hi:[0,1] neg_lo:[0,1] neg_hi:[0,1]
	v_pk_fma_f32 v[138:139], v[96:97], v[28:29], v[134:135] op_sel:[0,0,1] op_sel_hi:[1,1,0] neg_lo:[0,0,1] neg_hi:[0,0,1]
	v_pk_fma_f32 v[96:97], v[96:97], v[28:29], v[134:135] op_sel:[0,0,1] op_sel_hi:[1,1,0]
	v_pk_mul_f32 v[82:83], v[122:123], v[82:83]
	v_mov_b32_e32 v139, v97
	v_pk_fma_f32 v[96:97], v[122:123], v[28:29], v[82:83] op_sel:[0,0,1] op_sel_hi:[1,1,0] neg_lo:[0,0,1] neg_hi:[0,0,1]
	v_pk_fma_f32 v[28:29], v[122:123], v[28:29], v[82:83] op_sel:[0,0,1] op_sel_hi:[1,1,0]
	v_mov_b32_e32 v82, v96
	v_mov_b32_e32 v83, v29
	v_pk_mul_f32 v[28:29], v[106:107], v[28:29] op_sel:[1,1] op_sel_hi:[0,1]
	v_pk_fma_f32 v[134:135], v[106:107], v[96:97], v[28:29] neg_lo:[0,0,1] neg_hi:[0,0,1]
	v_pk_fma_f32 v[28:29], v[106:107], v[96:97], v[28:29] op_sel_hi:[1,0,1]
	v_add_u32_e32 v5, s57, v5
	v_mov_b32_e32 v135, v29
	v_pk_mul_f32 v[28:29], v[122:123], v[82:83]
	v_pk_mul_f32 v[82:83], v[122:123], v[82:83] op_sel:[1,0] op_sel_hi:[0,1]
	v_pk_add_f32 v[82:83], v[82:83], v[82:83] op_sel:[0,1] op_sel_hi:[0,1]
	v_pk_mul_f32 v[96:97], v[108:109], v[82:83]
	v_pk_add_f32 v[28:29], v[28:29], v[28:29] op_sel:[0,1] op_sel_hi:[0,1] neg_lo:[0,1] neg_hi:[0,1]
	v_pk_fma_f32 v[106:107], v[108:109], v[28:29], v[96:97] op_sel:[0,0,1] op_sel_hi:[1,1,0] neg_lo:[0,0,1] neg_hi:[0,0,1]
	v_pk_fma_f32 v[96:97], v[108:109], v[28:29], v[96:97] op_sel:[0,0,1] op_sel_hi:[1,1,0]
	v_pk_mul_f32 v[82:83], v[122:123], v[82:83]
	v_mov_b32_e32 v107, v97
	v_pk_fma_f32 v[96:97], v[122:123], v[28:29], v[82:83] op_sel:[0,0,1] op_sel_hi:[1,1,0] neg_lo:[0,0,1] neg_hi:[0,0,1]
	v_pk_fma_f32 v[28:29], v[122:123], v[28:29], v[82:83] op_sel:[0,0,1] op_sel_hi:[1,1,0]
	v_mov_b32_e32 v82, v96
	v_mov_b32_e32 v83, v29
	v_pk_mul_f32 v[28:29], v[110:111], v[28:29] op_sel:[1,1] op_sel_hi:[0,1]
	v_pk_fma_f32 v[108:109], v[110:111], v[96:97], v[28:29] neg_lo:[0,0,1] neg_hi:[0,0,1]
	v_pk_fma_f32 v[28:29], v[110:111], v[96:97], v[28:29] op_sel_hi:[1,0,1]
	v_add3_u32 v0, v5, v7, v0
	v_mov_b32_e32 v109, v29
	v_pk_mul_f32 v[28:29], v[122:123], v[82:83]
	v_pk_mul_f32 v[82:83], v[122:123], v[82:83] op_sel:[1,0] op_sel_hi:[0,1]
	v_pk_add_f32 v[82:83], v[82:83], v[82:83] op_sel:[0,1] op_sel_hi:[0,1]
	v_pk_mul_f32 v[96:97], v[114:115], v[82:83]
	v_pk_add_f32 v[28:29], v[28:29], v[28:29] op_sel:[0,1] op_sel_hi:[0,1] neg_lo:[0,1] neg_hi:[0,1]
	v_pk_fma_f32 v[110:111], v[114:115], v[28:29], v[96:97] op_sel:[0,0,1] op_sel_hi:[1,1,0] neg_lo:[0,0,1] neg_hi:[0,0,1]
	v_pk_fma_f32 v[96:97], v[114:115], v[28:29], v[96:97] op_sel:[0,0,1] op_sel_hi:[1,1,0]
	v_pk_mul_f32 v[82:83], v[122:123], v[82:83]
	v_mov_b32_e32 v111, v97
	v_pk_fma_f32 v[96:97], v[122:123], v[28:29], v[82:83] op_sel:[0,0,1] op_sel_hi:[1,1,0] neg_lo:[0,0,1] neg_hi:[0,0,1]
	v_pk_fma_f32 v[28:29], v[122:123], v[28:29], v[82:83] op_sel:[0,0,1] op_sel_hi:[1,1,0]
	v_mov_b32_e32 v82, v96
	v_mov_b32_e32 v83, v29
	s_waitcnt lgkmcnt(4)
	v_pk_mul_f32 v[28:29], v[124:125], v[28:29] op_sel:[1,1] op_sel_hi:[0,1]
	v_pk_fma_f32 v[114:115], v[124:125], v[96:97], v[28:29] neg_lo:[0,0,1] neg_hi:[0,0,1]
	v_pk_fma_f32 v[28:29], v[124:125], v[96:97], v[28:29] op_sel_hi:[1,0,1]
	s_nop 0
	v_mov_b32_e32 v115, v29
	v_pk_mul_f32 v[28:29], v[122:123], v[82:83]
	v_pk_mul_f32 v[82:83], v[122:123], v[82:83] op_sel:[1,0] op_sel_hi:[0,1]
	v_pk_add_f32 v[82:83], v[82:83], v[82:83] op_sel:[0,1] op_sel_hi:[0,1]
	s_waitcnt lgkmcnt(3)
	v_pk_mul_f32 v[96:97], v[126:127], v[82:83]
	v_pk_add_f32 v[28:29], v[28:29], v[28:29] op_sel:[0,1] op_sel_hi:[0,1] neg_lo:[0,1] neg_hi:[0,1]
	v_pk_fma_f32 v[124:125], v[126:127], v[28:29], v[96:97] op_sel:[0,0,1] op_sel_hi:[1,1,0] neg_lo:[0,0,1] neg_hi:[0,0,1]
	v_pk_fma_f32 v[96:97], v[126:127], v[28:29], v[96:97] op_sel:[0,0,1] op_sel_hi:[1,1,0]
	v_pk_mul_f32 v[82:83], v[122:123], v[82:83]
	v_mov_b32_e32 v125, v97
	v_pk_fma_f32 v[96:97], v[122:123], v[28:29], v[82:83] op_sel:[0,0,1] op_sel_hi:[1,1,0] neg_lo:[0,0,1] neg_hi:[0,0,1]
	v_pk_fma_f32 v[28:29], v[122:123], v[28:29], v[82:83] op_sel:[0,0,1] op_sel_hi:[1,1,0]
	v_mov_b32_e32 v82, v96
	v_mov_b32_e32 v83, v29
	s_waitcnt lgkmcnt(2)
	v_pk_mul_f32 v[28:29], v[128:129], v[28:29] op_sel:[1,1] op_sel_hi:[0,1]
	v_pk_fma_f32 v[126:127], v[128:129], v[96:97], v[28:29] neg_lo:[0,0,1] neg_hi:[0,0,1]
	v_pk_fma_f32 v[28:29], v[128:129], v[96:97], v[28:29] op_sel_hi:[1,0,1]
	s_nop 0
	v_mov_b32_e32 v127, v29
	v_pk_mul_f32 v[28:29], v[122:123], v[82:83]
	v_pk_mul_f32 v[82:83], v[122:123], v[82:83] op_sel:[1,0] op_sel_hi:[0,1]
	v_pk_add_f32 v[82:83], v[82:83], v[82:83] op_sel:[0,1] op_sel_hi:[0,1]
	s_waitcnt lgkmcnt(1)
	v_pk_mul_f32 v[96:97], v[130:131], v[82:83]
	v_pk_add_f32 v[28:29], v[28:29], v[28:29] op_sel:[0,1] op_sel_hi:[0,1] neg_lo:[0,1] neg_hi:[0,1]
	v_pk_fma_f32 v[128:129], v[130:131], v[28:29], v[96:97] op_sel:[0,0,1] op_sel_hi:[1,1,0] neg_lo:[0,0,1] neg_hi:[0,0,1]
	v_pk_fma_f32 v[96:97], v[130:131], v[28:29], v[96:97] op_sel:[0,0,1] op_sel_hi:[1,1,0]
	v_pk_mul_f32 v[82:83], v[122:123], v[82:83]
	v_mov_b32_e32 v129, v97
	v_pk_fma_f32 v[96:97], v[122:123], v[28:29], v[82:83] op_sel:[0,0,1] op_sel_hi:[1,1,0] neg_lo:[0,0,1] neg_hi:[0,0,1]
	v_pk_fma_f32 v[28:29], v[122:123], v[28:29], v[82:83] op_sel:[0,0,1] op_sel_hi:[1,1,0]
	v_mov_b32_e32 v82, v96
	v_mov_b32_e32 v83, v29
	s_waitcnt lgkmcnt(0)
	v_pk_mul_f32 v[28:29], v[132:133], v[28:29] op_sel:[1,1] op_sel_hi:[0,1]
	v_pk_fma_f32 v[130:131], v[132:133], v[96:97], v[28:29] neg_lo:[0,0,1] neg_hi:[0,0,1]
	v_pk_fma_f32 v[28:29], v[132:133], v[96:97], v[28:29] op_sel_hi:[1,0,1]
	s_nop 0
	v_mov_b32_e32 v131, v29
	v_pk_mul_f32 v[28:29], v[122:123], v[82:83]
	v_pk_mul_f32 v[82:83], v[122:123], v[82:83] op_sel:[1,0] op_sel_hi:[0,1]
	v_pk_add_f32 v[82:83], v[82:83], v[82:83] op_sel:[0,1] op_sel_hi:[0,1]
	v_pk_mul_f32 v[96:97], v[116:117], v[82:83]
	v_pk_add_f32 v[28:29], v[28:29], v[28:29] op_sel:[0,1] op_sel_hi:[0,1] neg_lo:[0,1] neg_hi:[0,1]
	v_pk_fma_f32 v[132:133], v[116:117], v[28:29], v[96:97] op_sel:[0,0,1] op_sel_hi:[1,1,0] neg_lo:[0,0,1] neg_hi:[0,0,1]
	v_pk_fma_f32 v[96:97], v[116:117], v[28:29], v[96:97] op_sel:[0,0,1] op_sel_hi:[1,1,0]
	v_pk_mul_f32 v[28:29], v[122:123], v[28:29]
	v_mov_b32_e32 v133, v97
	v_pk_fma_f32 v[96:97], v[122:123], v[82:83], v[28:29] op_sel:[0,0,1] op_sel_hi:[1,1,0] neg_lo:[1,0,0] neg_hi:[1,0,0]
	v_pk_fma_f32 v[28:29], v[122:123], v[82:83], v[28:29] op_sel:[0,0,1] op_sel_hi:[1,1,0]
	v_mov_b32_e32 v83, v97
	v_mov_b32_e32 v82, v28
	v_pk_mul_f32 v[116:117], v[118:119], v[28:29] op_sel:[1,0] op_sel_hi:[0,0]
	v_pk_mov_b32 v[28:29], v[96:97], v[28:29] op_sel:[1,0]
	v_pk_mul_f32 v[82:83], v[122:123], v[82:83]
	v_pk_mul_f32 v[28:29], v[122:123], v[28:29]
	v_pk_add_f32 v[82:83], v[82:83], v[82:83] op_sel:[1,0] op_sel_hi:[1,0]
	v_pk_fma_f32 v[142:143], v[118:119], v[96:97], v[116:117] op_sel:[0,1,0] neg_lo:[0,0,1] neg_hi:[0,0,1]
	v_pk_fma_f32 v[96:97], v[118:119], v[96:97], v[116:117] op_sel:[0,1,0]
	v_pk_mul_f32 v[82:83], v[120:121], v[82:83] op_sel:[1,0] op_sel_hi:[0,1]
	v_pk_add_f32 v[28:29], v[28:29], v[28:29] op_sel:[0,1] op_sel_hi:[0,1] neg_lo:[0,1] neg_hi:[0,1]
	v_mov_b32_e32 v143, v97
	v_pk_fma_f32 v[96:97], v[120:121], v[28:29], v[82:83] neg_lo:[0,0,1] neg_hi:[0,0,1]
	v_pk_fma_f32 v[28:29], v[120:121], v[28:29], v[82:83]
	v_pk_add_f32 v[82:83], v[134:135], v[130:131]
	v_mov_b32_e32 v97, v29
	v_pk_add_f32 v[28:29], v[26:27], v[114:115]
	v_pk_add_f32 v[26:27], v[26:27], v[114:115] neg_lo:[0,1] neg_hi:[0,1]
	v_pk_add_f32 v[114:115], v[134:135], v[130:131] neg_lo:[0,1] neg_hi:[0,1]
	v_pk_add_f32 v[120:121], v[106:107], v[132:133]
	v_xor_b32_e32 v117, 0x80000000, v114
	v_mov_b32_e32 v116, v115
	v_pk_add_f32 v[106:107], v[106:107], v[132:133] neg_lo:[0,1] neg_hi:[0,1]
	v_pk_add_f32 v[114:115], v[28:29], v[82:83]
	v_pk_add_f32 v[118:119], v[26:27], v[116:117]
	v_pk_add_f32 v[28:29], v[28:29], v[82:83] neg_lo:[0,1] neg_hi:[0,1]
	v_pk_add_f32 v[26:27], v[26:27], v[116:117] neg_lo:[0,1] neg_hi:[0,1]
	v_pk_add_f32 v[82:83], v[136:137], v[124:125]
	v_pk_add_f32 v[116:117], v[136:137], v[124:125] neg_lo:[0,1] neg_hi:[0,1]
	v_xor_b32_e32 v123, 0x80000000, v106
	v_mov_b32_e32 v122, v107
	v_pk_add_f32 v[106:107], v[82:83], v[120:121]
	v_pk_add_f32 v[124:125], v[116:117], v[122:123]
	v_pk_add_f32 v[82:83], v[82:83], v[120:121] neg_lo:[0,1] neg_hi:[0,1]
	v_pk_add_f32 v[116:117], v[116:117], v[122:123] neg_lo:[0,1] neg_hi:[0,1]
	v_pk_add_f32 v[120:121], v[140:141], v[126:127]
	v_pk_add_f32 v[122:123], v[140:141], v[126:127] neg_lo:[0,1] neg_hi:[0,1]
	v_pk_add_f32 v[126:127], v[108:109], v[142:143]
	v_pk_add_f32 v[108:109], v[108:109], v[142:143] neg_lo:[0,1] neg_hi:[0,1]
	s_nop 0
	v_xor_b32_e32 v131, 0x80000000, v108
	v_mov_b32_e32 v130, v109
	v_pk_add_f32 v[132:133], v[122:123], v[130:131]
	v_pk_add_f32 v[122:123], v[122:123], v[130:131] neg_lo:[0,1] neg_hi:[0,1]
	v_pk_add_f32 v[130:131], v[110:111], v[96:97]
	v_pk_add_f32 v[96:97], v[110:111], v[96:97] neg_lo:[0,1] neg_hi:[0,1]
	v_pk_add_f32 v[108:109], v[120:121], v[126:127]
	v_pk_add_f32 v[120:121], v[120:121], v[126:127] neg_lo:[0,1] neg_hi:[0,1]
	v_pk_add_f32 v[126:127], v[138:139], v[128:129]
	v_pk_add_f32 v[128:129], v[138:139], v[128:129] neg_lo:[0,1] neg_hi:[0,1]
	v_xor_b32_e32 v111, 0x80000000, v96
	v_mov_b32_e32 v110, v97
	v_pk_add_f32 v[134:135], v[128:129], v[110:111]
	v_pk_add_f32 v[110:111], v[128:129], v[110:111] neg_lo:[0,1] neg_hi:[0,1]
	v_pk_mul_f32 v[128:129], v[124:125], s[24:25] op_sel_hi:[1,0]
	v_pk_add_f32 v[96:97], v[126:127], v[130:131]
	v_pk_add_f32 v[126:127], v[126:127], v[130:131] neg_lo:[0,1] neg_hi:[0,1]
	v_pk_fma_f32 v[130:131], v[124:125], s[26:27], v[128:129] op_sel:[0,0,1] op_sel_hi:[1,0,0]
	v_pk_fma_f32 v[124:125], v[124:125], s[26:27], v[128:129] op_sel:[0,0,1] op_sel_hi:[1,0,0] neg_lo:[0,0,1] neg_hi:[0,0,1]
	s_nop 0
	v_mov_b32_e32 v131, v125
	v_pk_mul_f32 v[124:125], v[82:83], s[28:29] op_sel_hi:[1,0]
	s_nop 0
	v_pk_fma_f32 v[128:129], v[82:83], s[28:29], v[124:125] op_sel:[0,0,1] op_sel_hi:[1,0,0]
	v_pk_fma_f32 v[82:83], v[82:83], s[28:29], v[124:125] op_sel_hi:[1,0,0] neg_lo:[0,0,1] neg_hi:[0,0,1]
	v_pk_mul_f32 v[124:125], v[116:117], s[26:27] op_sel_hi:[1,0]
	v_mov_b32_e32 v129, v83
	v_pk_fma_f32 v[136:137], v[116:117], s[24:25], v[124:125] op_sel:[0,0,1] op_sel_hi:[1,0,0]
	v_pk_fma_f32 v[116:117], v[116:117], s[24:25], v[124:125] op_sel:[0,0,1] op_sel_hi:[1,0,0] neg_lo:[0,0,1] neg_hi:[0,0,1]
	s_nop 0
	v_mov_b32_e32 v137, v117
	v_pk_mul_f32 v[116:117], v[132:133], s[28:29] op_sel_hi:[1,0]
	s_nop 0
	v_pk_fma_f32 v[124:125], v[132:133], s[28:29], v[116:117] op_sel:[0,0,1] op_sel_hi:[1,0,0]
	v_pk_fma_f32 v[116:117], v[132:133], s[28:29], v[116:117] op_sel_hi:[1,0,0] neg_lo:[0,0,1] neg_hi:[0,0,1]
	s_nop 0
	v_mov_b32_e32 v125, v117
	v_pk_fma_f32 v[116:117], v[120:121], 0, v[120:121] op_sel:[0,0,1] op_sel_hi:[1,0,0]
	v_pk_fma_f32 v[120:121], v[120:121], 0, v[120:121] op_sel:[0,0,1] op_sel_hi:[1,0,0] neg_lo:[0,0,1] neg_hi:[0,0,1]
	s_nop 0
	v_mov_b32_e32 v117, v121
	v_pk_mul_f32 v[120:121], v[122:123], s[30:31] op_sel_hi:[1,0]
	s_nop 0
	v_pk_fma_f32 v[132:133], v[122:123], s[30:31], v[120:121] op_sel:[0,0,1] op_sel_hi:[1,0,0] neg_lo:[0,0,1] neg_hi:[0,0,1]
	v_pk_fma_f32 v[120:121], v[122:123], s[30:31], v[120:121] op_sel_hi:[1,0,0]
	v_pk_mul_f32 v[122:123], v[134:135], s[26:27] op_sel_hi:[1,0]
	v_mov_b32_e32 v133, v121
	v_pk_fma_f32 v[138:139], v[134:135], s[24:25], v[122:123] op_sel:[0,0,1] op_sel_hi:[1,0,0]
	v_pk_fma_f32 v[122:123], v[134:135], s[24:25], v[122:123] op_sel:[0,0,1] op_sel_hi:[1,0,0] neg_lo:[0,0,1] neg_hi:[0,0,1]
	v_pk_add_f32 v[120:121], v[26:27], v[132:133]
	v_mov_b32_e32 v139, v123
	v_pk_mul_f32 v[122:123], v[126:127], s[30:31] op_sel_hi:[1,0]
	v_pk_add_f32 v[26:27], v[26:27], v[132:133] neg_lo:[0,1] neg_hi:[0,1]
	v_pk_fma_f32 v[134:135], v[126:127], s[30:31], v[122:123] op_sel:[0,0,1] op_sel_hi:[1,0,0] neg_lo:[0,0,1] neg_hi:[0,0,1]
	v_pk_fma_f32 v[122:123], v[126:127], s[30:31], v[122:123] op_sel_hi:[1,0,0]
	s_nop 0
	v_mov_b32_e32 v135, v123
	v_pk_mul_f32 v[122:123], v[110:111], s[60:61] op_sel:[1,0]
	v_pk_add_f32 v[82:83], v[128:129], v[134:135]
	v_pk_fma_f32 v[110:111], v[110:111], s[34:35], v[122:123] op_sel_hi:[0,1,1]
	v_pk_add_f32 v[122:123], v[114:115], v[108:109]
	v_pk_add_f32 v[108:109], v[114:115], v[108:109] neg_lo:[0,1] neg_hi:[0,1]
	v_pk_add_f32 v[114:115], v[106:107], v[96:97]
	v_pk_add_f32 v[96:97], v[106:107], v[96:97] neg_lo:[0,1] neg_hi:[0,1]
	s_nop 0
	v_xor_b32_e32 v107, 0x80000000, v96
	v_mov_b32_e32 v106, v97
	v_pk_add_f32 v[96:97], v[122:123], v[114:115]
	v_pk_add_f32 v[126:127], v[108:109], v[106:107]
	v_pk_add_f32 v[114:115], v[122:123], v[114:115] neg_lo:[0,1] neg_hi:[0,1]
	v_pk_add_f32 v[106:107], v[108:109], v[106:107] neg_lo:[0,1] neg_hi:[0,1]
	v_pk_add_f32 v[108:109], v[118:119], v[124:125]
	v_pk_add_f32 v[118:119], v[118:119], v[124:125] neg_lo:[0,1] neg_hi:[0,1]
	v_pk_add_f32 v[122:123], v[130:131], v[138:139]
	v_pk_add_f32 v[124:125], v[130:131], v[138:139] neg_lo:[0,1] neg_hi:[0,1]
	s_nop 0
	v_xor_b32_e32 v131, 0x80000000, v124
	v_mov_b32_e32 v130, v125
	v_pk_add_f32 v[124:125], v[108:109], v[122:123]
	v_pk_add_f32 v[108:109], v[108:109], v[122:123] neg_lo:[0,1] neg_hi:[0,1]
	v_pk_add_f32 v[122:123], v[28:29], v[116:117]
	v_pk_add_f32 v[28:29], v[28:29], v[116:117] neg_lo:[0,1] neg_hi:[0,1]
	v_pk_add_f32 v[116:117], v[128:129], v[134:135] neg_lo:[0,1] neg_hi:[0,1]
	v_pk_add_f32 v[138:139], v[118:119], v[130:131]
	v_xor_b32_e32 v129, 0x80000000, v116
	v_mov_b32_e32 v128, v117
	v_pk_add_f32 v[116:117], v[122:123], v[82:83]
	v_pk_add_f32 v[82:83], v[122:123], v[82:83] neg_lo:[0,1] neg_hi:[0,1]
	v_pk_add_f32 v[122:123], v[136:137], v[110:111]
	v_pk_add_f32 v[110:111], v[136:137], v[110:111] neg_lo:[0,1] neg_hi:[0,1]
	v_pk_add_f32 v[118:119], v[118:119], v[130:131] neg_lo:[0,1] neg_hi:[0,1]
	v_pk_add_f32 v[130:131], v[28:29], v[128:129]
	v_pk_add_f32 v[28:29], v[28:29], v[128:129] neg_lo:[0,1] neg_hi:[0,1]
	v_xor_b32_e32 v129, 0x80000000, v110
	v_mov_b32_e32 v128, v111
	v_pk_add_f32 v[110:111], v[120:121], v[122:123]
	v_pk_add_f32 v[132:133], v[26:27], v[128:129]
	v_pk_add_f32 v[120:121], v[120:121], v[122:123] neg_lo:[0,1] neg_hi:[0,1]
	v_pk_add_f32 v[26:27], v[26:27], v[128:129] neg_lo:[0,1] neg_hi:[0,1]
	ds_write_b64 v0, v[96:97]
	ds_write_b64 v0, v[124:125] offset:2176
	ds_write_b64 v0, v[116:117] offset:4352
	ds_write_b64 v0, v[110:111] offset:6528
	ds_write_b64 v0, v[126:127] offset:8704
	ds_write_b64 v0, v[138:139] offset:10880
	ds_write_b64 v0, v[130:131] offset:13056
	ds_write_b64 v0, v[132:133] offset:15232
	ds_write_b64 v0, v[114:115] offset:17408
	ds_write_b64 v0, v[108:109] offset:19584
	ds_write_b64 v0, v[82:83] offset:21760
	ds_write_b64 v0, v[120:121] offset:23936
	ds_write_b64 v0, v[106:107] offset:26112
	ds_write_b64 v0, v[118:119] offset:28288
	ds_write_b64 v0, v[28:29] offset:30464
	ds_write_b64 v0, v[26:27] offset:32640

.LBB0_358:
	s_or_b64 exec, exec, s[2:3]
	v_mov_b32_e32 v200, v180
	s_waitcnt lgkmcnt(0)
	s_barrier
	s_nop 0
	v_cmp_gt_i32_e32 vcc, s56, v200
	s_and_saveexec_b64 s[2:3], vcc
	s_cbranch_execz .LBB0_360
	v_ashrrev_i32_e32 v181, 31, v200
	v_add_u32_sdwa v181, v200, v181 dst_sel:DWORD dst_unused:UNUSED_PAD src0_sel:DWORD src1_sel:BYTE_3
	v_ashrrev_i32_e32 v181, 8, v181
	v_mul_i32_i24_e32 v201, 0x100, v181
	v_sub_u32_e32 v200, v200, v201
	v_ashrrev_i16_e32 v201, 15, v200
	v_lshrrev_b16_e32 v201, 12, v201
	v_add_u16_e32 v201, v200, v201
	v_ashrrev_i16_e32 v233, 4, v201
	v_and_b32_e32 v201, -16, v201
	v_mul_i32_i24_e32 v181, 0x1100, v181
	v_sub_u16_e32 v204, v200, v201
	v_lshlrev_b32_e32 v234, 3, v181
	v_lshlrev_b32_e32 v201, 3, v200
	v_ashrrev_i32_e32 v200, 4, v200
	v_add_u32_e32 v181, s57, v234
	v_lshlrev_b32_e32 v200, 3, v200
	v_add3_u32 v181, v181, v201, v200
	v_bfe_i32 v235, v204, 0, 16
	ds_read_b64 v[200:201], v181
	ds_read_b64 v[202:203], v181 offset:2176
	ds_read_b64 v[214:215], v181 offset:4352
	ds_read_b64 v[216:217], v181 offset:6528
	ds_read_b64 v[218:219], v181 offset:8704
	ds_read_b64 v[222:223], v181 offset:10880
	ds_read_b64 v[224:225], v181 offset:13056
	ds_read_b64 v[226:227], v181 offset:15232
	ds_read_b64 v[228:229], v181 offset:17408
	ds_read_b64 v[230:231], v181 offset:19584
	ds_read_b64 v[236:237], v181 offset:21760
	ds_read_b64 v[238:239], v181 offset:23936
	ds_read_b64 v[242:243], v181 offset:26112
	ds_read_b64 v[244:245], v181 offset:28288
	ds_read_b64 v[246:247], v181 offset:30464
	ds_read_b64 v[206:207], v181 offset:32640
	v_mad_i32_i24 v181, v235, s27, 0
	v_add_u32_e32 v204, 0x808, v181
	ds_read2_b64 v[210:213], v204 offset1:1
	s_mov_b32 s61, s34
	s_mov_b32 s35, s24
	s_waitcnt lgkmcnt(0)
	v_pk_mul_f32 v[204:205], v[202:203], v[210:211] op_sel:[1,1] op_sel_hi:[1,0]
	s_nop 0
	v_pk_fma_f32 v[208:209], v[202:203], v[210:211], v[204:205] op_sel_hi:[0,1,1] neg_lo:[0,0,1]
	v_pk_mul_f32 v[202:203], v[214:215], v[212:213] op_sel:[1,1] op_sel_hi:[1,0]
	s_nop 0
	v_pk_fma_f32 v[204:205], v[214:215], v[212:213], v[202:203] neg_lo:[0,0,1] neg_hi:[0,0,1]
	v_pk_fma_f32 v[202:203], v[214:215], v[212:213], v[202:203] op_sel_hi:[0,1,1]
	v_add_u32_e32 v202, 0x818, v181
	ds_read2_b64 v[210:213], v202 offset1:1
	v_mov_b32_e32 v205, v203
	s_waitcnt lgkmcnt(0)
	v_pk_mul_f32 v[214:215], v[216:217], v[210:211] op_sel:[1,1] op_sel_hi:[1,0]
	s_nop 0
	v_pk_fma_f32 v[202:203], v[216:217], v[210:211], v[214:215] op_sel_hi:[0,1,1] neg_lo:[0,0,1]
	v_pk_mul_f32 v[210:211], v[218:219], v[212:213] op_sel:[1,1] op_sel_hi:[1,0]
	s_nop 0
	v_pk_fma_f32 v[216:217], v[218:219], v[212:213], v[210:211] neg_lo:[0,0,1] neg_hi:[0,0,1]
	v_pk_fma_f32 v[210:211], v[218:219], v[212:213], v[210:211] op_sel_hi:[0,1,1]
	v_add_u32_e32 v210, 0x828, v181
	ds_read2_b64 v[218:221], v210 offset1:1
	v_mov_b32_e32 v217, v211
	s_waitcnt lgkmcnt(0)
	v_pk_mul_f32 v[210:211], v[222:223], v[218:219] op_sel:[1,1] op_sel_hi:[1,0]
	s_nop 0
	v_pk_fma_f32 v[214:215], v[222:223], v[218:219], v[210:211] op_sel_hi:[0,1,1] neg_lo:[0,0,1]
	v_pk_mul_f32 v[210:211], v[224:225], v[220:221] op_sel:[1,1] op_sel_hi:[1,0]
	s_nop 0
	v_pk_fma_f32 v[212:213], v[224:225], v[220:221], v[210:211] neg_lo:[0,0,1] neg_hi:[0,0,1]
	v_pk_fma_f32 v[210:211], v[224:225], v[220:221], v[210:211] op_sel_hi:[0,1,1]
	v_add_u32_e32 v210, 0x838, v181
	ds_read2_b64 v[218:221], v210 offset1:1
	v_mov_b32_e32 v213, v211
	s_waitcnt lgkmcnt(0)
	v_pk_mul_f32 v[222:223], v[226:227], v[218:219] op_sel:[1,1] op_sel_hi:[1,0]
	s_nop 0
	v_pk_fma_f32 v[210:211], v[226:227], v[218:219], v[222:223] op_sel_hi:[0,1,1] neg_lo:[0,0,1]
	v_pk_mul_f32 v[218:219], v[228:229], v[220:221] op_sel:[1,1] op_sel_hi:[1,0]
	s_nop 0
	v_pk_fma_f32 v[224:225], v[228:229], v[220:221], v[218:219] neg_lo:[0,0,1] neg_hi:[0,0,1]
	v_pk_fma_f32 v[218:219], v[228:229], v[220:221], v[218:219] op_sel_hi:[0,1,1]
	v_add_u32_e32 v218, 0x848, v181
	ds_read2_b64 v[226:229], v218 offset1:1
	v_mov_b32_e32 v225, v219
	s_waitcnt lgkmcnt(0)
	v_pk_mul_f32 v[218:219], v[230:231], v[226:227] op_sel:[1,1] op_sel_hi:[1,0]
	s_nop 0
	v_pk_fma_f32 v[222:223], v[230:231], v[226:227], v[218:219] op_sel_hi:[0,1,1] neg_lo:[0,0,1]
	v_pk_mul_f32 v[218:219], v[236:237], v[228:229] op_sel:[1,1] op_sel_hi:[1,0]
	s_nop 0
	v_pk_fma_f32 v[220:221], v[236:237], v[228:229], v[218:219] neg_lo:[0,0,1] neg_hi:[0,0,1]
	v_pk_fma_f32 v[218:219], v[236:237], v[228:229], v[218:219] op_sel_hi:[0,1,1]
	v_add_u32_e32 v218, 0x858, v181
	ds_read2_b64 v[226:229], v218 offset1:1
	v_mov_b32_e32 v221, v219
	s_waitcnt lgkmcnt(0)
	v_pk_mul_f32 v[230:231], v[238:239], v[226:227] op_sel:[1,1] op_sel_hi:[1,0]
	s_nop 0
	v_pk_fma_f32 v[218:219], v[238:239], v[226:227], v[230:231] op_sel_hi:[0,1,1] neg_lo:[0,0,1]
	v_pk_mul_f32 v[226:227], v[242:243], v[228:229] op_sel:[1,1] op_sel_hi:[1,0]
	s_nop 0
	v_pk_fma_f32 v[230:231], v[242:243], v[228:229], v[226:227] neg_lo:[0,0,1] neg_hi:[0,0,1]
	v_pk_fma_f32 v[226:227], v[242:243], v[228:229], v[226:227] op_sel_hi:[0,1,1]
	v_add_u32_e32 v226, 0x868, v181
	ds_read2_b64 v[236:239], v226 offset1:1
	v_mov_b32_e32 v231, v227
	s_waitcnt lgkmcnt(0)
	v_pk_mul_f32 v[226:227], v[244:245], v[236:237] op_sel:[1,1] op_sel_hi:[1,0]
	s_nop 0
	v_pk_fma_f32 v[228:229], v[244:245], v[236:237], v[226:227] op_sel_hi:[0,1,1] neg_lo:[0,0,1]
	v_pk_mul_f32 v[236:237], v[246:247], v[238:239] op_sel:[1,1] op_sel_hi:[1,0]
	v_pk_fma_f32 v[226:227], v[246:247], v[238:239], v[236:237] op_sel_hi:[0,1,1] neg_lo:[0,0,1]
	ds_read_b64 v[236:237], v181 offset:2168
	v_bfe_i32 v181, v233, 0, 16
	v_lshl_add_u32 v181, v181, 8, v235
	s_waitcnt lgkmcnt(0)
	v_pk_mul_f32 v[238:239], v[206:207], v[236:237] op_sel:[1,1] op_sel_hi:[1,0]
	s_nop 0
	v_pk_fma_f32 v[242:243], v[206:207], v[236:237], v[238:239] op_sel_hi:[0,1,1] neg_lo:[0,0,1]
	v_pk_add_f32 v[206:207], v[200:201], v[224:225]
	v_pk_add_f32 v[200:201], v[200:201], v[224:225] neg_lo:[0,1] neg_hi:[0,1]
	v_pk_add_f32 v[224:225], v[216:217], v[230:231]
	v_pk_add_f32 v[216:217], v[216:217], v[230:231] neg_lo:[0,1] neg_hi:[0,1]
	s_nop 0
	v_xor_b32_e32 v231, 0x80000000, v216
	v_mov_b32_e32 v230, v217
	v_pk_add_f32 v[216:217], v[206:207], v[224:225]
	v_pk_add_f32 v[206:207], v[206:207], v[224:225] neg_lo:[0,1] neg_hi:[0,1]
	v_pk_add_f32 v[224:225], v[208:209], v[222:223]
	v_pk_add_f32 v[208:209], v[208:209], v[222:223] neg_lo:[0,1] neg_hi:[0,1]
	v_pk_add_f32 v[222:223], v[214:215], v[228:229]
	v_pk_add_f32 v[214:215], v[214:215], v[228:229] neg_lo:[0,1] neg_hi:[0,1]
	v_pk_add_f32 v[236:237], v[200:201], v[230:231]
	v_xor_b32_e32 v229, 0x80000000, v214
	v_mov_b32_e32 v228, v215
	v_pk_add_f32 v[214:215], v[224:225], v[222:223]
	v_pk_add_f32 v[222:223], v[224:225], v[222:223] neg_lo:[0,1] neg_hi:[0,1]
	v_pk_add_f32 v[224:225], v[204:205], v[220:221]
	v_pk_add_f32 v[204:205], v[204:205], v[220:221] neg_lo:[0,1] neg_hi:[0,1]
	v_pk_add_f32 v[220:221], v[212:213], v[226:227]
	v_pk_add_f32 v[212:213], v[212:213], v[226:227] neg_lo:[0,1] neg_hi:[0,1]
	v_pk_add_f32 v[200:201], v[200:201], v[230:231] neg_lo:[0,1] neg_hi:[0,1]
	v_pk_add_f32 v[230:231], v[208:209], v[228:229]
	v_xor_b32_e32 v227, 0x80000000, v212
	v_mov_b32_e32 v226, v213
	v_pk_add_f32 v[212:213], v[224:225], v[220:221]
	v_pk_add_f32 v[220:221], v[224:225], v[220:221] neg_lo:[0,1] neg_hi:[0,1]
	v_pk_add_f32 v[224:225], v[202:203], v[218:219]
	v_pk_add_f32 v[202:203], v[202:203], v[218:219] neg_lo:[0,1] neg_hi:[0,1]
	v_pk_add_f32 v[218:219], v[210:211], v[242:243]
	v_pk_add_f32 v[210:211], v[210:211], v[242:243] neg_lo:[0,1] neg_hi:[0,1]
	v_pk_add_f32 v[208:209], v[208:209], v[228:229] neg_lo:[0,1] neg_hi:[0,1]
	v_pk_add_f32 v[228:229], v[204:205], v[226:227]
	v_pk_add_f32 v[204:205], v[204:205], v[226:227] neg_lo:[0,1] neg_hi:[0,1]
	v_xor_b32_e32 v227, 0x80000000, v210
	v_mov_b32_e32 v226, v211
	v_pk_add_f32 v[210:211], v[224:225], v[218:219]
	v_pk_add_f32 v[218:219], v[224:225], v[218:219] neg_lo:[0,1] neg_hi:[0,1]
	v_pk_mul_f32 v[224:225], v[230:231], s[24:25] op_sel_hi:[1,0]
	v_pk_add_f32 v[238:239], v[202:203], v[226:227]
	v_pk_add_f32 v[202:203], v[202:203], v[226:227] neg_lo:[0,1] neg_hi:[0,1]
	v_pk_fma_f32 v[226:227], v[230:231], s[26:27], v[224:225] op_sel:[0,0,1] op_sel_hi:[1,0,0]
	v_pk_fma_f32 v[224:225], v[230:231], s[26:27], v[224:225] op_sel:[0,0,1] op_sel_hi:[1,0,0] neg_lo:[0,0,1] neg_hi:[0,0,1]
	s_nop 0
	v_mov_b32_e32 v227, v225
	v_pk_mul_f32 v[224:225], v[222:223], s[28:29] op_sel_hi:[1,0]
	s_nop 0
	v_pk_fma_f32 v[230:231], v[222:223], s[28:29], v[224:225] op_sel:[0,0,1] op_sel_hi:[1,0,0]
	v_pk_fma_f32 v[222:223], v[222:223], s[28:29], v[224:225] op_sel_hi:[1,0,0] neg_lo:[0,0,1] neg_hi:[0,0,1]
	v_pk_mul_f32 v[224:225], v[208:209], s[26:27] op_sel_hi:[1,0]
	v_mov_b32_e32 v231, v223
	v_pk_fma_f32 v[242:243], v[208:209], s[24:25], v[224:225] op_sel:[0,0,1] op_sel_hi:[1,0,0]
	v_pk_fma_f32 v[208:209], v[208:209], s[24:25], v[224:225] op_sel:[0,0,1] op_sel_hi:[1,0,0] neg_lo:[0,0,1] neg_hi:[0,0,1]
	s_nop 0
	v_mov_b32_e32 v243, v209
	v_pk_mul_f32 v[208:209], v[228:229], s[28:29] op_sel_hi:[1,0]
	s_nop 0
	v_pk_fma_f32 v[224:225], v[228:229], s[28:29], v[208:209] op_sel:[0,0,1] op_sel_hi:[1,0,0]
	v_pk_fma_f32 v[208:209], v[228:229], s[28:29], v[208:209] op_sel_hi:[1,0,0] neg_lo:[0,0,1] neg_hi:[0,0,1]
	s_nop 0
	v_mov_b32_e32 v225, v209
	v_pk_fma_f32 v[208:209], v[220:221], 0, v[220:221] op_sel:[0,0,1] op_sel_hi:[1,0,0]
	v_pk_fma_f32 v[220:221], v[220:221], 0, v[220:221] op_sel:[0,0,1] op_sel_hi:[1,0,0] neg_lo:[0,0,1] neg_hi:[0,0,1]
	s_nop 0
	v_mov_b32_e32 v209, v221
	v_pk_mul_f32 v[220:221], v[204:205], s[30:31] op_sel_hi:[1,0]
	s_nop 0
	v_pk_fma_f32 v[228:229], v[204:205], s[30:31], v[220:221] op_sel:[0,0,1] op_sel_hi:[1,0,0] neg_lo:[0,0,1] neg_hi:[0,0,1]
	v_pk_fma_f32 v[204:205], v[204:205], s[30:31], v[220:221] op_sel_hi:[1,0,0]
	v_pk_mul_f32 v[220:221], v[238:239], s[26:27] op_sel_hi:[1,0]
	v_mov_b32_e32 v229, v205
	v_pk_fma_f32 v[244:245], v[238:239], s[24:25], v[220:221] op_sel:[0,0,1] op_sel_hi:[1,0,0]
	v_pk_fma_f32 v[220:221], v[238:239], s[24:25], v[220:221] op_sel:[0,0,1] op_sel_hi:[1,0,0] neg_lo:[0,0,1] neg_hi:[0,0,1]
	v_pk_add_f32 v[204:205], v[200:201], v[228:229]
	v_mov_b32_e32 v245, v221
	v_pk_mul_f32 v[220:221], v[218:219], s[30:31] op_sel_hi:[1,0]
	v_pk_add_f32 v[200:201], v[200:201], v[228:229] neg_lo:[0,1] neg_hi:[0,1]
	v_pk_fma_f32 v[238:239], v[218:219], s[30:31], v[220:221] op_sel:[0,0,1] op_sel_hi:[1,0,0] neg_lo:[0,0,1] neg_hi:[0,0,1]
	v_pk_fma_f32 v[218:219], v[218:219], s[30:31], v[220:221] op_sel_hi:[1,0,0]
	s_nop 0
	v_mov_b32_e32 v239, v219
	v_pk_mul_f32 v[218:219], v[202:203], s[60:61] op_sel:[1,0]
	v_pk_add_f32 v[222:223], v[230:231], v[238:239] neg_lo:[0,1] neg_hi:[0,1]
	v_pk_fma_f32 v[202:203], v[202:203], s[34:35], v[218:219] op_sel_hi:[0,1,1]
	v_pk_add_f32 v[218:219], v[216:217], v[212:213]
	v_pk_add_f32 v[212:213], v[216:217], v[212:213] neg_lo:[0,1] neg_hi:[0,1]
	v_pk_add_f32 v[216:217], v[214:215], v[210:211]
	v_pk_add_f32 v[210:211], v[214:215], v[210:211] neg_lo:[0,1] neg_hi:[0,1]
	s_nop 0
	v_xor_b32_e32 v215, 0x80000000, v210
	v_mov_b32_e32 v214, v211
	v_pk_add_f32 v[210:211], v[218:219], v[216:217]
	v_pk_add_f32 v[220:221], v[212:213], v[214:215]
	v_pk_add_f32 v[216:217], v[218:219], v[216:217] neg_lo:[0,1] neg_hi:[0,1]
	v_pk_add_f32 v[212:213], v[212:213], v[214:215] neg_lo:[0,1] neg_hi:[0,1]
	v_pk_add_f32 v[214:215], v[236:237], v[224:225]
	v_pk_add_f32 v[218:219], v[236:237], v[224:225] neg_lo:[0,1] neg_hi:[0,1]
	v_pk_add_f32 v[224:225], v[226:227], v[244:245]
	v_pk_add_f32 v[226:227], v[226:227], v[244:245] neg_lo:[0,1] neg_hi:[0,1]
	s_nop 0
	v_xor_b32_e32 v237, 0x80000000, v226
	v_mov_b32_e32 v236, v227
	v_pk_add_f32 v[226:227], v[214:215], v[224:225]
	v_pk_add_f32 v[214:215], v[214:215], v[224:225] neg_lo:[0,1] neg_hi:[0,1]
	v_pk_add_f32 v[224:225], v[206:207], v[208:209]
	v_pk_add_f32 v[206:207], v[206:207], v[208:209] neg_lo:[0,1] neg_hi:[0,1]
	v_pk_add_f32 v[208:209], v[230:231], v[238:239]
	v_xor_b32_e32 v231, 0x80000000, v222
	v_mov_b32_e32 v230, v223
	v_pk_add_f32 v[222:223], v[224:225], v[208:209]
	v_pk_add_f32 v[208:209], v[224:225], v[208:209] neg_lo:[0,1] neg_hi:[0,1]
	v_pk_add_f32 v[224:225], v[242:243], v[202:203]
	v_pk_add_f32 v[202:203], v[242:243], v[202:203] neg_lo:[0,1] neg_hi:[0,1]
	v_pk_add_f32 v[244:245], v[218:219], v[236:237]
	v_xor_b32_e32 v229, 0x80000000, v202
	v_mov_b32_e32 v228, v203
	v_pk_add_f32 v[202:203], v[204:205], v[224:225]
	v_pk_add_f32 v[204:205], v[204:205], v[224:225] neg_lo:[0,1] neg_hi:[0,1]
	v_lshlrev_b32_e32 v225, 3, v181
	v_ashrrev_i32_e32 v181, 4, v181
	v_add_u32_e32 v224, 0, v234
	v_lshlrev_b32_e32 v181, 3, v181
	v_add3_u32 v181, v224, v225, v181
	v_pk_add_f32 v[218:219], v[218:219], v[236:237] neg_lo:[0,1] neg_hi:[0,1]
	v_pk_add_f32 v[236:237], v[206:207], v[230:231]
	v_pk_add_f32 v[206:207], v[206:207], v[230:231] neg_lo:[0,1] neg_hi:[0,1]
	v_pk_add_f32 v[230:231], v[200:201], v[228:229]
	v_pk_add_f32 v[200:201], v[200:201], v[228:229] neg_lo:[0,1] neg_hi:[0,1]
	v_add_u32_e32 v224, 0x1800, v181
	v_add_u32_e32 v181, 0x1c00, v181
	ds_write2_b64 v224, v[210:211], v[226:227] offset0:16 offset1:33
	ds_write2_b64 v224, v[222:223], v[202:203] offset0:50 offset1:67
	ds_write2_b64 v224, v[220:221], v[244:245] offset0:84 offset1:101
	ds_write2_b64 v224, v[236:237], v[230:231] offset0:118 offset1:135
	ds_write2_b64 v224, v[216:217], v[214:215] offset0:152 offset1:169
	ds_write2_b64 v224, v[208:209], v[204:205] offset0:186 offset1:203
	ds_write2_b64 v224, v[212:213], v[218:219] offset0:220 offset1:237
	ds_write2_b64 v181, v[206:207], v[200:201] offset0:126 offset1:143
.LBB0_360:
	s_or_b64 exec, exec, s[2:3]
	v_mov_b32_e32 v200, v180
	s_waitcnt lgkmcnt(0)
	s_barrier
	s_nop 0
	v_cmp_gt_i32_e32 vcc, s56, v200
	s_and_saveexec_b64 s[2:3], vcc
	s_cbranch_execz .LBB0_362
	v_ashrrev_i32_e32 v181, 31, v200
	v_add_u32_sdwa v181, v200, v181 dst_sel:DWORD dst_unused:UNUSED_PAD src0_sel:DWORD src1_sel:BYTE_3
	v_ashrrev_i32_e32 v181, 8, v181
	v_mul_i32_i24_e32 v201, 0x100, v181
	v_sub_u32_e32 v200, v200, v201
	v_mul_i32_i24_e32 v181, 0x1100, v181
	v_lshlrev_b32_e32 v233, 3, v200
	v_ashrrev_i32_e32 v200, 4, v200
	v_lshlrev_b32_e32 v181, 3, v181
	v_lshlrev_b32_e32 v248, 3, v200
	v_add_u32_e32 v222, 0, v233
	v_add3_u32 v234, v222, v181, v248
	ds_read_b64 v[200:201], v234 offset:6272
	ds_read_b64 v[202:203], v234 offset:8448
	ds_read_b64 v[204:205], v234 offset:10624
	ds_read_b64 v[206:207], v234 offset:12800
	ds_read_b64 v[208:209], v234 offset:14976
	ds_read_b64 v[210:211], v234 offset:17152
	ds_read_b64 v[212:213], v234 offset:19328
	ds_read_b64 v[214:215], v234 offset:21504
	ds_read_b64 v[216:217], v234 offset:34560
	ds_read_b64 v[218:219], v234 offset:36736
	ds_read_b64 v[220:221], v234 offset:38912
	ds_read_b64 v[222:223], v222
	ds_read_b64 v[224:225], v234 offset:23680
	ds_read_b64 v[226:227], v234 offset:25856
	ds_read_b64 v[228:229], v234 offset:28032
	ds_read_b64 v[230:231], v234 offset:30208
	ds_read_b64 v[234:235], v234 offset:32384
	s_waitcnt lgkmcnt(5)
	v_pk_mul_f32 v[236:237], v[202:203], v[222:223] op_sel:[1,1] op_sel_hi:[1,0]
	s_mov_b32 s61, s34
	v_pk_fma_f32 v[238:239], v[202:203], v[222:223], v[236:237] op_sel_hi:[0,1,1] neg_lo:[0,0,1]
	v_pk_mul_f32 v[202:203], v[222:223], v[222:223] op_sel:[1,1] op_sel_hi:[1,0]
	s_mov_b32 s35, s24
	v_pk_fma_f32 v[236:237], v[222:223], v[222:223], v[202:203] op_sel_hi:[1,0,1] neg_lo:[0,0,1] neg_hi:[0,0,1]
	v_pk_fma_f32 v[202:203], v[222:223], v[222:223], v[202:203] op_sel_hi:[1,0,1]
	v_mov_b32_e32 v242, v236
	v_mov_b32_e32 v243, v203
	v_pk_mul_f32 v[202:203], v[204:205], v[202:203] op_sel:[1,1] op_sel_hi:[0,1]
	v_pk_fma_f32 v[244:245], v[204:205], v[236:237], v[202:203] neg_lo:[0,0,1] neg_hi:[0,0,1]
	v_pk_fma_f32 v[202:203], v[204:205], v[236:237], v[202:203] op_sel_hi:[1,0,1]
	v_pk_mul_f32 v[204:205], v[222:223], v[242:243] op_sel:[1,0] op_sel_hi:[0,1]
	v_mov_b32_e32 v245, v203
	v_pk_mul_f32 v[202:203], v[222:223], v[242:243]
	v_pk_add_f32 v[204:205], v[204:205], v[204:205] op_sel:[0,1] op_sel_hi:[0,1]
	v_pk_mul_f32 v[236:237], v[206:207], v[204:205]
	v_pk_add_f32 v[202:203], v[202:203], v[202:203] op_sel:[0,1] op_sel_hi:[0,1] neg_lo:[0,1] neg_hi:[0,1]
	v_pk_fma_f32 v[242:243], v[206:207], v[202:203], v[236:237] op_sel:[0,0,1] op_sel_hi:[1,1,0] neg_lo:[0,0,1] neg_hi:[0,0,1]
	v_pk_fma_f32 v[206:207], v[206:207], v[202:203], v[236:237] op_sel:[0,0,1] op_sel_hi:[1,1,0]
	v_pk_mul_f32 v[204:205], v[222:223], v[204:205]
	v_mov_b32_e32 v243, v207
	v_pk_fma_f32 v[206:207], v[222:223], v[202:203], v[204:205] op_sel:[0,0,1] op_sel_hi:[1,1,0] neg_lo:[0,0,1] neg_hi:[0,0,1]
	v_pk_fma_f32 v[202:203], v[222:223], v[202:203], v[204:205] op_sel:[0,0,1] op_sel_hi:[1,1,0]
	v_mov_b32_e32 v204, v206
	v_mov_b32_e32 v205, v203
	v_pk_mul_f32 v[202:203], v[208:209], v[202:203] op_sel:[1,1] op_sel_hi:[0,1]
	v_pk_fma_f32 v[236:237], v[208:209], v[206:207], v[202:203] neg_lo:[0,0,1] neg_hi:[0,0,1]
	v_pk_fma_f32 v[202:203], v[208:209], v[206:207], v[202:203] op_sel_hi:[1,0,1]
	v_add_u32_e32 v181, s57, v181
	v_mov_b32_e32 v237, v203
	v_pk_mul_f32 v[202:203], v[222:223], v[204:205]
	v_pk_mul_f32 v[204:205], v[222:223], v[204:205] op_sel:[1,0] op_sel_hi:[0,1]
	v_pk_add_f32 v[204:205], v[204:205], v[204:205] op_sel:[0,1] op_sel_hi:[0,1]
	v_pk_mul_f32 v[206:207], v[210:211], v[204:205]
	v_pk_add_f32 v[202:203], v[202:203], v[202:203] op_sel:[0,1] op_sel_hi:[0,1] neg_lo:[0,1] neg_hi:[0,1]
	v_pk_fma_f32 v[208:209], v[210:211], v[202:203], v[206:207] op_sel:[0,0,1] op_sel_hi:[1,1,0] neg_lo:[0,0,1] neg_hi:[0,0,1]
	v_pk_fma_f32 v[206:207], v[210:211], v[202:203], v[206:207] op_sel:[0,0,1] op_sel_hi:[1,1,0]
	v_pk_mul_f32 v[204:205], v[222:223], v[204:205]
	v_mov_b32_e32 v209, v207
	v_pk_fma_f32 v[206:207], v[222:223], v[202:203], v[204:205] op_sel:[0,0,1] op_sel_hi:[1,1,0] neg_lo:[0,0,1] neg_hi:[0,0,1]
	v_pk_fma_f32 v[202:203], v[222:223], v[202:203], v[204:205] op_sel:[0,0,1] op_sel_hi:[1,1,0]
	v_mov_b32_e32 v204, v206
	v_mov_b32_e32 v205, v203
	v_pk_mul_f32 v[202:203], v[212:213], v[202:203] op_sel:[1,1] op_sel_hi:[0,1]
	v_pk_fma_f32 v[210:211], v[212:213], v[206:207], v[202:203] neg_lo:[0,0,1] neg_hi:[0,0,1]
	v_pk_fma_f32 v[202:203], v[212:213], v[206:207], v[202:203] op_sel_hi:[1,0,1]
	v_add3_u32 v181, v181, v233, v248
	v_mov_b32_e32 v211, v203
	v_pk_mul_f32 v[202:203], v[222:223], v[204:205]
	v_pk_mul_f32 v[204:205], v[222:223], v[204:205] op_sel:[1,0] op_sel_hi:[0,1]
	v_pk_add_f32 v[204:205], v[204:205], v[204:205] op_sel:[0,1] op_sel_hi:[0,1]
	v_pk_mul_f32 v[206:207], v[214:215], v[204:205]
	v_pk_add_f32 v[202:203], v[202:203], v[202:203] op_sel:[0,1] op_sel_hi:[0,1] neg_lo:[0,1] neg_hi:[0,1]
	v_pk_fma_f32 v[212:213], v[214:215], v[202:203], v[206:207] op_sel:[0,0,1] op_sel_hi:[1,1,0] neg_lo:[0,0,1] neg_hi:[0,0,1]
	v_pk_fma_f32 v[206:207], v[214:215], v[202:203], v[206:207] op_sel:[0,0,1] op_sel_hi:[1,1,0]
	v_pk_mul_f32 v[204:205], v[222:223], v[204:205]
	v_mov_b32_e32 v213, v207
	v_pk_fma_f32 v[206:207], v[222:223], v[202:203], v[204:205] op_sel:[0,0,1] op_sel_hi:[1,1,0] neg_lo:[0,0,1] neg_hi:[0,0,1]
	v_pk_fma_f32 v[202:203], v[222:223], v[202:203], v[204:205] op_sel:[0,0,1] op_sel_hi:[1,1,0]
	v_mov_b32_e32 v204, v206
	v_mov_b32_e32 v205, v203
	s_waitcnt lgkmcnt(4)
	v_pk_mul_f32 v[202:203], v[224:225], v[202:203] op_sel:[1,1] op_sel_hi:[0,1]
	v_pk_fma_f32 v[214:215], v[224:225], v[206:207], v[202:203] neg_lo:[0,0,1] neg_hi:[0,0,1]
	v_pk_fma_f32 v[202:203], v[224:225], v[206:207], v[202:203] op_sel_hi:[1,0,1]
	s_nop 0
	v_mov_b32_e32 v215, v203
	v_pk_mul_f32 v[202:203], v[222:223], v[204:205]
	v_pk_mul_f32 v[204:205], v[222:223], v[204:205] op_sel:[1,0] op_sel_hi:[0,1]
	v_pk_add_f32 v[204:205], v[204:205], v[204:205] op_sel:[0,1] op_sel_hi:[0,1]
	s_waitcnt lgkmcnt(3)
	v_pk_mul_f32 v[206:207], v[226:227], v[204:205]
	v_pk_add_f32 v[202:203], v[202:203], v[202:203] op_sel:[0,1] op_sel_hi:[0,1] neg_lo:[0,1] neg_hi:[0,1]
	v_pk_fma_f32 v[224:225], v[226:227], v[202:203], v[206:207] op_sel:[0,0,1] op_sel_hi:[1,1,0] neg_lo:[0,0,1] neg_hi:[0,0,1]
	v_pk_fma_f32 v[206:207], v[226:227], v[202:203], v[206:207] op_sel:[0,0,1] op_sel_hi:[1,1,0]
	v_pk_mul_f32 v[204:205], v[222:223], v[204:205]
	v_mov_b32_e32 v225, v207
	v_pk_fma_f32 v[206:207], v[222:223], v[202:203], v[204:205] op_sel:[0,0,1] op_sel_hi:[1,1,0] neg_lo:[0,0,1] neg_hi:[0,0,1]
	v_pk_fma_f32 v[202:203], v[222:223], v[202:203], v[204:205] op_sel:[0,0,1] op_sel_hi:[1,1,0]
	v_mov_b32_e32 v204, v206
	v_mov_b32_e32 v205, v203
	s_waitcnt lgkmcnt(2)
	v_pk_mul_f32 v[202:203], v[228:229], v[202:203] op_sel:[1,1] op_sel_hi:[0,1]
	v_pk_fma_f32 v[226:227], v[228:229], v[206:207], v[202:203] neg_lo:[0,0,1] neg_hi:[0,0,1]
	v_pk_fma_f32 v[202:203], v[228:229], v[206:207], v[202:203] op_sel_hi:[1,0,1]
	s_nop 0
	v_mov_b32_e32 v227, v203
	v_pk_mul_f32 v[202:203], v[222:223], v[204:205]
	v_pk_mul_f32 v[204:205], v[222:223], v[204:205] op_sel:[1,0] op_sel_hi:[0,1]
	v_pk_add_f32 v[204:205], v[204:205], v[204:205] op_sel:[0,1] op_sel_hi:[0,1]
	s_waitcnt lgkmcnt(1)
	v_pk_mul_f32 v[206:207], v[230:231], v[204:205]
	v_pk_add_f32 v[202:203], v[202:203], v[202:203] op_sel:[0,1] op_sel_hi:[0,1] neg_lo:[0,1] neg_hi:[0,1]
	v_pk_fma_f32 v[228:229], v[230:231], v[202:203], v[206:207] op_sel:[0,0,1] op_sel_hi:[1,1,0] neg_lo:[0,0,1] neg_hi:[0,0,1]
	v_pk_fma_f32 v[206:207], v[230:231], v[202:203], v[206:207] op_sel:[0,0,1] op_sel_hi:[1,1,0]
	v_pk_mul_f32 v[204:205], v[222:223], v[204:205]
	v_mov_b32_e32 v229, v207
	v_pk_fma_f32 v[206:207], v[222:223], v[202:203], v[204:205] op_sel:[0,0,1] op_sel_hi:[1,1,0] neg_lo:[0,0,1] neg_hi:[0,0,1]
	v_pk_fma_f32 v[202:203], v[222:223], v[202:203], v[204:205] op_sel:[0,0,1] op_sel_hi:[1,1,0]
	v_mov_b32_e32 v204, v206
	v_mov_b32_e32 v205, v203
	s_waitcnt lgkmcnt(0)
	v_pk_mul_f32 v[202:203], v[234:235], v[202:203] op_sel:[1,1] op_sel_hi:[0,1]
	v_pk_fma_f32 v[230:231], v[234:235], v[206:207], v[202:203] neg_lo:[0,0,1] neg_hi:[0,0,1]
	v_pk_fma_f32 v[202:203], v[234:235], v[206:207], v[202:203] op_sel_hi:[1,0,1]
	s_nop 0
	v_mov_b32_e32 v231, v203
	v_pk_mul_f32 v[202:203], v[222:223], v[204:205]
	v_pk_mul_f32 v[204:205], v[222:223], v[204:205] op_sel:[1,0] op_sel_hi:[0,1]
	v_pk_add_f32 v[204:205], v[204:205], v[204:205] op_sel:[0,1] op_sel_hi:[0,1]
	v_pk_mul_f32 v[206:207], v[216:217], v[204:205]
	v_pk_add_f32 v[202:203], v[202:203], v[202:203] op_sel:[0,1] op_sel_hi:[0,1] neg_lo:[0,1] neg_hi:[0,1]
	v_pk_fma_f32 v[234:235], v[216:217], v[202:203], v[206:207] op_sel:[0,0,1] op_sel_hi:[1,1,0] neg_lo:[0,0,1] neg_hi:[0,0,1]
	v_pk_fma_f32 v[206:207], v[216:217], v[202:203], v[206:207] op_sel:[0,0,1] op_sel_hi:[1,1,0]
	v_pk_mul_f32 v[202:203], v[222:223], v[202:203]
	v_mov_b32_e32 v235, v207
	v_pk_fma_f32 v[206:207], v[222:223], v[204:205], v[202:203] op_sel:[0,0,1] op_sel_hi:[1,1,0] neg_lo:[1,0,0] neg_hi:[1,0,0]
	v_pk_fma_f32 v[202:203], v[222:223], v[204:205], v[202:203] op_sel:[0,0,1] op_sel_hi:[1,1,0]
	v_mov_b32_e32 v205, v207
	v_mov_b32_e32 v204, v202
	v_pk_mul_f32 v[216:217], v[218:219], v[202:203] op_sel:[1,0] op_sel_hi:[0,0]
	v_pk_mov_b32 v[202:203], v[206:207], v[202:203] op_sel:[1,0]
	v_pk_mul_f32 v[204:205], v[222:223], v[204:205]
	v_pk_mul_f32 v[202:203], v[222:223], v[202:203]
	v_pk_add_f32 v[204:205], v[204:205], v[204:205] op_sel:[1,0] op_sel_hi:[1,0]
	v_pk_fma_f32 v[246:247], v[218:219], v[206:207], v[216:217] op_sel:[0,1,0] neg_lo:[0,0,1] neg_hi:[0,0,1]
	v_pk_fma_f32 v[206:207], v[218:219], v[206:207], v[216:217] op_sel:[0,1,0]
	v_pk_mul_f32 v[204:205], v[220:221], v[204:205] op_sel:[1,0] op_sel_hi:[0,1]
	v_pk_add_f32 v[202:203], v[202:203], v[202:203] op_sel:[0,1] op_sel_hi:[0,1] neg_lo:[0,1] neg_hi:[0,1]
	v_mov_b32_e32 v247, v207
	v_pk_fma_f32 v[206:207], v[220:221], v[202:203], v[204:205] neg_lo:[0,0,1] neg_hi:[0,0,1]
	v_pk_fma_f32 v[202:203], v[220:221], v[202:203], v[204:205]
	v_pk_add_f32 v[204:205], v[236:237], v[230:231]
	v_mov_b32_e32 v207, v203
	v_pk_add_f32 v[202:203], v[200:201], v[214:215]
	v_pk_add_f32 v[200:201], v[200:201], v[214:215] neg_lo:[0,1] neg_hi:[0,1]
	v_pk_add_f32 v[214:215], v[236:237], v[230:231] neg_lo:[0,1] neg_hi:[0,1]
	v_pk_add_f32 v[220:221], v[208:209], v[234:235]
	v_xor_b32_e32 v217, 0x80000000, v214
	v_mov_b32_e32 v216, v215
	v_pk_add_f32 v[208:209], v[208:209], v[234:235] neg_lo:[0,1] neg_hi:[0,1]
	v_pk_add_f32 v[214:215], v[202:203], v[204:205]
	v_pk_add_f32 v[218:219], v[200:201], v[216:217]
	v_pk_add_f32 v[202:203], v[202:203], v[204:205] neg_lo:[0,1] neg_hi:[0,1]
	v_pk_add_f32 v[200:201], v[200:201], v[216:217] neg_lo:[0,1] neg_hi:[0,1]
	v_pk_add_f32 v[204:205], v[238:239], v[224:225]
	v_pk_add_f32 v[216:217], v[238:239], v[224:225] neg_lo:[0,1] neg_hi:[0,1]
	v_xor_b32_e32 v223, 0x80000000, v208
	v_mov_b32_e32 v222, v209
	v_pk_add_f32 v[208:209], v[204:205], v[220:221]
	v_pk_add_f32 v[224:225], v[216:217], v[222:223]
	v_pk_add_f32 v[204:205], v[204:205], v[220:221] neg_lo:[0,1] neg_hi:[0,1]
	v_pk_add_f32 v[216:217], v[216:217], v[222:223] neg_lo:[0,1] neg_hi:[0,1]
	v_pk_add_f32 v[220:221], v[244:245], v[226:227]
	v_pk_add_f32 v[222:223], v[244:245], v[226:227] neg_lo:[0,1] neg_hi:[0,1]
	v_pk_add_f32 v[226:227], v[210:211], v[246:247]
	v_pk_add_f32 v[210:211], v[210:211], v[246:247] neg_lo:[0,1] neg_hi:[0,1]
	s_nop 0
	v_xor_b32_e32 v231, 0x80000000, v210
	v_mov_b32_e32 v230, v211
	v_pk_add_f32 v[234:235], v[222:223], v[230:231]
	v_pk_add_f32 v[222:223], v[222:223], v[230:231] neg_lo:[0,1] neg_hi:[0,1]
	v_pk_add_f32 v[230:231], v[212:213], v[206:207]
	v_pk_add_f32 v[206:207], v[212:213], v[206:207] neg_lo:[0,1] neg_hi:[0,1]
	v_pk_add_f32 v[210:211], v[220:221], v[226:227]
	v_pk_add_f32 v[220:221], v[220:221], v[226:227] neg_lo:[0,1] neg_hi:[0,1]
	v_pk_add_f32 v[226:227], v[242:243], v[228:229]
	v_pk_add_f32 v[228:229], v[242:243], v[228:229] neg_lo:[0,1] neg_hi:[0,1]
	v_xor_b32_e32 v213, 0x80000000, v206
	v_mov_b32_e32 v212, v207
	v_pk_add_f32 v[236:237], v[228:229], v[212:213]
	v_pk_add_f32 v[212:213], v[228:229], v[212:213] neg_lo:[0,1] neg_hi:[0,1]
	v_pk_mul_f32 v[228:229], v[224:225], s[24:25] op_sel_hi:[1,0]
	v_pk_add_f32 v[206:207], v[226:227], v[230:231]
	v_pk_add_f32 v[226:227], v[226:227], v[230:231] neg_lo:[0,1] neg_hi:[0,1]
	v_pk_fma_f32 v[230:231], v[224:225], s[26:27], v[228:229] op_sel:[0,0,1] op_sel_hi:[1,0,0]
	v_pk_fma_f32 v[224:225], v[224:225], s[26:27], v[228:229] op_sel:[0,0,1] op_sel_hi:[1,0,0] neg_lo:[0,0,1] neg_hi:[0,0,1]
	s_nop 0
	v_mov_b32_e32 v231, v225
	v_pk_mul_f32 v[224:225], v[204:205], s[28:29] op_sel_hi:[1,0]
	s_nop 0
	v_pk_fma_f32 v[228:229], v[204:205], s[28:29], v[224:225] op_sel:[0,0,1] op_sel_hi:[1,0,0]
	v_pk_fma_f32 v[204:205], v[204:205], s[28:29], v[224:225] op_sel_hi:[1,0,0] neg_lo:[0,0,1] neg_hi:[0,0,1]
	v_pk_mul_f32 v[224:225], v[216:217], s[26:27] op_sel_hi:[1,0]
	v_mov_b32_e32 v229, v205
	v_pk_fma_f32 v[238:239], v[216:217], s[24:25], v[224:225] op_sel:[0,0,1] op_sel_hi:[1,0,0]
	v_pk_fma_f32 v[216:217], v[216:217], s[24:25], v[224:225] op_sel:[0,0,1] op_sel_hi:[1,0,0] neg_lo:[0,0,1] neg_hi:[0,0,1]
	s_nop 0
	v_mov_b32_e32 v239, v217
	v_pk_mul_f32 v[216:217], v[234:235], s[28:29] op_sel_hi:[1,0]
	s_nop 0
	v_pk_fma_f32 v[224:225], v[234:235], s[28:29], v[216:217] op_sel:[0,0,1] op_sel_hi:[1,0,0]
	v_pk_fma_f32 v[216:217], v[234:235], s[28:29], v[216:217] op_sel_hi:[1,0,0] neg_lo:[0,0,1] neg_hi:[0,0,1]
	s_nop 0
	v_mov_b32_e32 v225, v217
	v_pk_fma_f32 v[216:217], v[220:221], 0, v[220:221] op_sel:[0,0,1] op_sel_hi:[1,0,0]
	v_pk_fma_f32 v[220:221], v[220:221], 0, v[220:221] op_sel:[0,0,1] op_sel_hi:[1,0,0] neg_lo:[0,0,1] neg_hi:[0,0,1]
	s_nop 0
	v_mov_b32_e32 v217, v221
	v_pk_mul_f32 v[220:221], v[222:223], s[30:31] op_sel_hi:[1,0]
	s_nop 0
	v_pk_fma_f32 v[234:235], v[222:223], s[30:31], v[220:221] op_sel:[0,0,1] op_sel_hi:[1,0,0] neg_lo:[0,0,1] neg_hi:[0,0,1]
	v_pk_fma_f32 v[220:221], v[222:223], s[30:31], v[220:221] op_sel_hi:[1,0,0]
	v_pk_mul_f32 v[222:223], v[236:237], s[26:27] op_sel_hi:[1,0]
	v_mov_b32_e32 v235, v221
	v_pk_fma_f32 v[242:243], v[236:237], s[24:25], v[222:223] op_sel:[0,0,1] op_sel_hi:[1,0,0]
	v_pk_fma_f32 v[222:223], v[236:237], s[24:25], v[222:223] op_sel:[0,0,1] op_sel_hi:[1,0,0] neg_lo:[0,0,1] neg_hi:[0,0,1]
	v_pk_add_f32 v[220:221], v[200:201], v[234:235]
	v_mov_b32_e32 v243, v223
	v_pk_mul_f32 v[222:223], v[226:227], s[30:31] op_sel_hi:[1,0]
	v_pk_add_f32 v[200:201], v[200:201], v[234:235] neg_lo:[0,1] neg_hi:[0,1]
	v_pk_fma_f32 v[236:237], v[226:227], s[30:31], v[222:223] op_sel:[0,0,1] op_sel_hi:[1,0,0] neg_lo:[0,0,1] neg_hi:[0,0,1]
	v_pk_fma_f32 v[222:223], v[226:227], s[30:31], v[222:223] op_sel_hi:[1,0,0]
	s_nop 0
	v_mov_b32_e32 v237, v223
	v_pk_mul_f32 v[222:223], v[212:213], s[60:61] op_sel:[1,0]
	v_pk_add_f32 v[204:205], v[228:229], v[236:237]
	v_pk_fma_f32 v[212:213], v[212:213], s[34:35], v[222:223] op_sel_hi:[0,1,1]
	v_pk_add_f32 v[222:223], v[214:215], v[210:211]
	v_pk_add_f32 v[210:211], v[214:215], v[210:211] neg_lo:[0,1] neg_hi:[0,1]
	v_pk_add_f32 v[214:215], v[208:209], v[206:207]
	v_pk_add_f32 v[206:207], v[208:209], v[206:207] neg_lo:[0,1] neg_hi:[0,1]
	s_nop 0
	v_xor_b32_e32 v209, 0x80000000, v206
	v_mov_b32_e32 v208, v207
	v_pk_add_f32 v[206:207], v[222:223], v[214:215]
	v_pk_add_f32 v[226:227], v[210:211], v[208:209]
	v_pk_add_f32 v[214:215], v[222:223], v[214:215] neg_lo:[0,1] neg_hi:[0,1]
	v_pk_add_f32 v[208:209], v[210:211], v[208:209] neg_lo:[0,1] neg_hi:[0,1]
	v_pk_add_f32 v[210:211], v[218:219], v[224:225]
	v_pk_add_f32 v[218:219], v[218:219], v[224:225] neg_lo:[0,1] neg_hi:[0,1]
	v_pk_add_f32 v[222:223], v[230:231], v[242:243]
	v_pk_add_f32 v[224:225], v[230:231], v[242:243] neg_lo:[0,1] neg_hi:[0,1]
	s_nop 0
	v_xor_b32_e32 v231, 0x80000000, v224
	v_mov_b32_e32 v230, v225
	v_pk_add_f32 v[224:225], v[210:211], v[222:223]
	v_pk_add_f32 v[210:211], v[210:211], v[222:223] neg_lo:[0,1] neg_hi:[0,1]
	v_pk_add_f32 v[222:223], v[202:203], v[216:217]
	v_pk_add_f32 v[202:203], v[202:203], v[216:217] neg_lo:[0,1] neg_hi:[0,1]
	v_pk_add_f32 v[216:217], v[228:229], v[236:237] neg_lo:[0,1] neg_hi:[0,1]
	v_pk_add_f32 v[242:243], v[218:219], v[230:231]
	v_xor_b32_e32 v229, 0x80000000, v216
	v_mov_b32_e32 v228, v217
	v_pk_add_f32 v[216:217], v[222:223], v[204:205]
	v_pk_add_f32 v[204:205], v[222:223], v[204:205] neg_lo:[0,1] neg_hi:[0,1]
	v_pk_add_f32 v[222:223], v[238:239], v[212:213]
	v_pk_add_f32 v[212:213], v[238:239], v[212:213] neg_lo:[0,1] neg_hi:[0,1]
	v_pk_add_f32 v[218:219], v[218:219], v[230:231] neg_lo:[0,1] neg_hi:[0,1]
	v_pk_add_f32 v[230:231], v[202:203], v[228:229]
	v_pk_add_f32 v[202:203], v[202:203], v[228:229] neg_lo:[0,1] neg_hi:[0,1]
	v_xor_b32_e32 v229, 0x80000000, v212
	v_mov_b32_e32 v228, v213
	v_pk_add_f32 v[212:213], v[220:221], v[222:223]
	v_pk_add_f32 v[234:235], v[200:201], v[228:229]
	v_pk_add_f32 v[220:221], v[220:221], v[222:223] neg_lo:[0,1] neg_hi:[0,1]
	v_pk_add_f32 v[200:201], v[200:201], v[228:229] neg_lo:[0,1] neg_hi:[0,1]
	ds_write_b64 v181, v[206:207]
	ds_write_b64 v181, v[224:225] offset:2176
	ds_write_b64 v181, v[216:217] offset:4352
	ds_write_b64 v181, v[212:213] offset:6528
	ds_write_b64 v181, v[226:227] offset:8704
	ds_write_b64 v181, v[242:243] offset:10880
	ds_write_b64 v181, v[230:231] offset:13056
	ds_write_b64 v181, v[234:235] offset:15232
	ds_write_b64 v181, v[214:215] offset:17408
	ds_write_b64 v181, v[210:211] offset:19584
	ds_write_b64 v181, v[204:205] offset:21760
	ds_write_b64 v181, v[220:221] offset:23936
	ds_write_b64 v181, v[208:209] offset:26112
	ds_write_b64 v181, v[218:219] offset:28288
	ds_write_b64 v181, v[202:203] offset:30464
	ds_write_b64 v181, v[200:201] offset:32640

.LBB0_370:
	s_or_b64 exec, exec, s[2:3]
	v_mov_b32_e32 v200, v180
	s_waitcnt lgkmcnt(0)
	s_barrier
	s_nop 0
	v_cmp_gt_i32_e32 vcc, s56, v200
	s_and_saveexec_b64 s[2:3], vcc
	s_cbranch_execz .LBB0_372
	v_ashrrev_i32_e32 v181, 31, v200
	v_add_u32_sdwa v181, v200, v181 dst_sel:DWORD dst_unused:UNUSED_PAD src0_sel:DWORD src1_sel:BYTE_3
	v_ashrrev_i32_e32 v181, 8, v181
	v_mul_i32_i24_e32 v201, 0x100, v181
	v_sub_u32_e32 v200, v200, v201
	v_ashrrev_i16_e32 v201, 15, v200
	v_lshrrev_b16_e32 v201, 12, v201
	v_add_u16_e32 v201, v200, v201
	v_ashrrev_i16_e32 v237, 4, v201
	v_and_b32_e32 v201, -16, v201
	v_mul_i32_i24_e32 v181, 0x1100, v181
	v_sub_u16_e32 v204, v200, v201
	v_lshlrev_b32_e32 v238, 3, v181
	v_lshlrev_b32_e32 v201, 3, v200
	v_ashrrev_i32_e32 v200, 4, v200
	v_add_u32_e32 v181, s57, v238
	v_lshlrev_b32_e32 v200, 3, v200
	v_add3_u32 v181, v181, v201, v200
	v_bfe_i32 v239, v204, 0, 16
	ds_read_b64 v[200:201], v181
	ds_read_b64 v[202:203], v181 offset:2176
	ds_read_b64 v[214:215], v181 offset:4352
	ds_read_b64 v[216:217], v181 offset:6528
	ds_read_b64 v[218:219], v181 offset:8704
	ds_read_b64 v[222:223], v181 offset:10880
	ds_read_b64 v[224:225], v181 offset:13056
	ds_read_b64 v[226:227], v181 offset:15232
	ds_read_b64 v[228:229], v181 offset:17408
	ds_read_b64 v[230:231], v181 offset:19584
	ds_read_b64 v[242:243], v181 offset:21760
	ds_read_b64 v[244:245], v181 offset:23936
	ds_read_b64 v[246:247], v181 offset:26112
	ds_read_b64 v[248:249], v181 offset:28288
	ds_read_b64 v[250:251], v181 offset:30464
	ds_read_b64 v[206:207], v181 offset:32640
	v_mad_i32_i24 v181, v239, s27, 0
	v_add_u32_e32 v204, 0x808, v181
	ds_read2_b64 v[210:213], v204 offset1:1
	s_mov_b32 s61, s34
	s_mov_b32 s35, s24
	s_waitcnt lgkmcnt(0)
	v_pk_mul_f32 v[204:205], v[202:203], v[210:211] op_sel:[1,1] op_sel_hi:[1,0]
	s_nop 0
	v_pk_fma_f32 v[208:209], v[202:203], v[210:211], v[204:205] op_sel_hi:[0,1,1] neg_lo:[0,0,1]
	v_pk_mul_f32 v[202:203], v[214:215], v[212:213] op_sel:[1,1] op_sel_hi:[1,0]
	s_nop 0
	v_pk_fma_f32 v[204:205], v[214:215], v[212:213], v[202:203] neg_lo:[0,0,1] neg_hi:[0,0,1]
	v_pk_fma_f32 v[202:203], v[214:215], v[212:213], v[202:203] op_sel_hi:[0,1,1]
	v_add_u32_e32 v202, 0x818, v181
	ds_read2_b64 v[210:213], v202 offset1:1
	v_mov_b32_e32 v205, v203
	s_waitcnt lgkmcnt(0)
	v_pk_mul_f32 v[214:215], v[216:217], v[210:211] op_sel:[1,1] op_sel_hi:[1,0]
	s_nop 0
	v_pk_fma_f32 v[202:203], v[216:217], v[210:211], v[214:215] op_sel_hi:[0,1,1] neg_lo:[0,0,1]
	v_pk_mul_f32 v[210:211], v[218:219], v[212:213] op_sel:[1,1] op_sel_hi:[1,0]
	s_nop 0
	v_pk_fma_f32 v[216:217], v[218:219], v[212:213], v[210:211] neg_lo:[0,0,1] neg_hi:[0,0,1]
	v_pk_fma_f32 v[210:211], v[218:219], v[212:213], v[210:211] op_sel_hi:[0,1,1]
	v_add_u32_e32 v210, 0x828, v181
	ds_read2_b64 v[218:221], v210 offset1:1
	v_mov_b32_e32 v217, v211
	s_waitcnt lgkmcnt(0)
	v_pk_mul_f32 v[210:211], v[222:223], v[218:219] op_sel:[1,1] op_sel_hi:[1,0]
	s_nop 0
	v_pk_fma_f32 v[214:215], v[222:223], v[218:219], v[210:211] op_sel_hi:[0,1,1] neg_lo:[0,0,1]
	v_pk_mul_f32 v[210:211], v[224:225], v[220:221] op_sel:[1,1] op_sel_hi:[1,0]
	s_nop 0
	v_pk_fma_f32 v[212:213], v[224:225], v[220:221], v[210:211] neg_lo:[0,0,1] neg_hi:[0,0,1]
	v_pk_fma_f32 v[210:211], v[224:225], v[220:221], v[210:211] op_sel_hi:[0,1,1]
	v_add_u32_e32 v210, 0x838, v181
	ds_read2_b64 v[218:221], v210 offset1:1
	v_mov_b32_e32 v213, v211
	s_waitcnt lgkmcnt(0)
	v_pk_mul_f32 v[222:223], v[226:227], v[218:219] op_sel:[1,1] op_sel_hi:[1,0]
	s_nop 0
	v_pk_fma_f32 v[210:211], v[226:227], v[218:219], v[222:223] op_sel_hi:[0,1,1] neg_lo:[0,0,1]
	v_pk_mul_f32 v[218:219], v[228:229], v[220:221] op_sel:[1,1] op_sel_hi:[1,0]
	s_nop 0
	v_pk_fma_f32 v[224:225], v[228:229], v[220:221], v[218:219] neg_lo:[0,0,1] neg_hi:[0,0,1]
	v_pk_fma_f32 v[218:219], v[228:229], v[220:221], v[218:219] op_sel_hi:[0,1,1]
	v_add_u32_e32 v218, 0x848, v181
	ds_read2_b64 v[226:229], v218 offset1:1
	v_mov_b32_e32 v225, v219
	s_waitcnt lgkmcnt(0)
	v_pk_mul_f32 v[218:219], v[230:231], v[226:227] op_sel:[1,1] op_sel_hi:[1,0]
	s_nop 0
	v_pk_fma_f32 v[222:223], v[230:231], v[226:227], v[218:219] op_sel_hi:[0,1,1] neg_lo:[0,0,1]
	v_pk_mul_f32 v[218:219], v[242:243], v[228:229] op_sel:[1,1] op_sel_hi:[1,0]
	s_nop 0
	v_pk_fma_f32 v[220:221], v[242:243], v[228:229], v[218:219] neg_lo:[0,0,1] neg_hi:[0,0,1]
	v_pk_fma_f32 v[218:219], v[242:243], v[228:229], v[218:219] op_sel_hi:[0,1,1]
	v_add_u32_e32 v218, 0x858, v181
	ds_read2_b64 v[226:229], v218 offset1:1
	v_mov_b32_e32 v221, v219
	s_waitcnt lgkmcnt(0)
	v_pk_mul_f32 v[230:231], v[244:245], v[226:227] op_sel:[1,1] op_sel_hi:[1,0]
	s_nop 0
	v_pk_fma_f32 v[218:219], v[244:245], v[226:227], v[230:231] op_sel_hi:[0,1,1] neg_lo:[0,0,1]
	v_pk_mul_f32 v[226:227], v[246:247], v[228:229] op_sel:[1,1] op_sel_hi:[1,0]
	s_nop 0
	v_pk_fma_f32 v[230:231], v[246:247], v[228:229], v[226:227] neg_lo:[0,0,1] neg_hi:[0,0,1]
	v_pk_fma_f32 v[226:227], v[246:247], v[228:229], v[226:227] op_sel_hi:[0,1,1]
	v_add_u32_e32 v226, 0x868, v181
	ds_read2_b64 v[242:245], v226 offset1:1
	v_mov_b32_e32 v231, v227
	s_waitcnt lgkmcnt(0)
	v_pk_mul_f32 v[226:227], v[248:249], v[242:243] op_sel:[1,1] op_sel_hi:[1,0]
	s_nop 0
	v_pk_fma_f32 v[228:229], v[248:249], v[242:243], v[226:227] op_sel_hi:[0,1,1] neg_lo:[0,0,1]
	v_pk_mul_f32 v[242:243], v[250:251], v[244:245] op_sel:[1,1] op_sel_hi:[1,0]
	v_pk_fma_f32 v[226:227], v[250:251], v[244:245], v[242:243] op_sel_hi:[0,1,1] neg_lo:[0,0,1]
	ds_read_b64 v[242:243], v181 offset:2168
	v_bfe_i32 v181, v237, 0, 16
	v_lshl_add_u32 v181, v181, 8, v239
	s_waitcnt lgkmcnt(0)
	v_pk_mul_f32 v[244:245], v[206:207], v[242:243] op_sel:[1,1] op_sel_hi:[1,0]
	s_nop 0
	v_pk_fma_f32 v[246:247], v[206:207], v[242:243], v[244:245] op_sel_hi:[0,1,1] neg_lo:[0,0,1]
	v_pk_add_f32 v[206:207], v[200:201], v[224:225]
	v_pk_add_f32 v[200:201], v[200:201], v[224:225] neg_lo:[0,1] neg_hi:[0,1]
	v_pk_add_f32 v[224:225], v[216:217], v[230:231]
	v_pk_add_f32 v[216:217], v[216:217], v[230:231] neg_lo:[0,1] neg_hi:[0,1]
	s_nop 0
	v_xor_b32_e32 v231, 0x80000000, v216
	v_mov_b32_e32 v230, v217
	v_pk_add_f32 v[216:217], v[206:207], v[224:225]
	v_pk_add_f32 v[206:207], v[206:207], v[224:225] neg_lo:[0,1] neg_hi:[0,1]
	v_pk_add_f32 v[224:225], v[208:209], v[222:223]
	v_pk_add_f32 v[208:209], v[208:209], v[222:223] neg_lo:[0,1] neg_hi:[0,1]
	v_pk_add_f32 v[222:223], v[214:215], v[228:229]
	v_pk_add_f32 v[214:215], v[214:215], v[228:229] neg_lo:[0,1] neg_hi:[0,1]
	v_pk_add_f32 v[242:243], v[200:201], v[230:231]
	v_xor_b32_e32 v229, 0x80000000, v214
	v_mov_b32_e32 v228, v215
	v_pk_add_f32 v[214:215], v[224:225], v[222:223]
	v_pk_add_f32 v[222:223], v[224:225], v[222:223] neg_lo:[0,1] neg_hi:[0,1]
	v_pk_add_f32 v[224:225], v[204:205], v[220:221]
	v_pk_add_f32 v[204:205], v[204:205], v[220:221] neg_lo:[0,1] neg_hi:[0,1]
	v_pk_add_f32 v[220:221], v[212:213], v[226:227]
	v_pk_add_f32 v[212:213], v[212:213], v[226:227] neg_lo:[0,1] neg_hi:[0,1]
	v_pk_add_f32 v[200:201], v[200:201], v[230:231] neg_lo:[0,1] neg_hi:[0,1]
	v_pk_add_f32 v[230:231], v[208:209], v[228:229]
	v_xor_b32_e32 v227, 0x80000000, v212
	v_mov_b32_e32 v226, v213
	v_pk_add_f32 v[212:213], v[224:225], v[220:221]
	v_pk_add_f32 v[220:221], v[224:225], v[220:221] neg_lo:[0,1] neg_hi:[0,1]
	v_pk_add_f32 v[224:225], v[202:203], v[218:219]
	v_pk_add_f32 v[202:203], v[202:203], v[218:219] neg_lo:[0,1] neg_hi:[0,1]
	v_pk_add_f32 v[218:219], v[210:211], v[246:247]
	v_pk_add_f32 v[210:211], v[210:211], v[246:247] neg_lo:[0,1] neg_hi:[0,1]
	v_pk_add_f32 v[208:209], v[208:209], v[228:229] neg_lo:[0,1] neg_hi:[0,1]
	v_pk_add_f32 v[228:229], v[204:205], v[226:227]
	v_pk_add_f32 v[204:205], v[204:205], v[226:227] neg_lo:[0,1] neg_hi:[0,1]
	v_xor_b32_e32 v227, 0x80000000, v210
	v_mov_b32_e32 v226, v211
	v_pk_add_f32 v[210:211], v[224:225], v[218:219]
	v_pk_add_f32 v[218:219], v[224:225], v[218:219] neg_lo:[0,1] neg_hi:[0,1]
	v_pk_mul_f32 v[224:225], v[230:231], s[24:25] op_sel_hi:[1,0]
	v_pk_add_f32 v[244:245], v[202:203], v[226:227]
	v_pk_add_f32 v[202:203], v[202:203], v[226:227] neg_lo:[0,1] neg_hi:[0,1]
	v_pk_fma_f32 v[226:227], v[230:231], s[26:27], v[224:225] op_sel:[0,0,1] op_sel_hi:[1,0,0]
	v_pk_fma_f32 v[224:225], v[230:231], s[26:27], v[224:225] op_sel:[0,0,1] op_sel_hi:[1,0,0] neg_lo:[0,0,1] neg_hi:[0,0,1]
	s_nop 0
	v_mov_b32_e32 v227, v225
	v_pk_mul_f32 v[224:225], v[222:223], s[28:29] op_sel_hi:[1,0]
	s_nop 0
	v_pk_fma_f32 v[230:231], v[222:223], s[28:29], v[224:225] op_sel:[0,0,1] op_sel_hi:[1,0,0]
	v_pk_fma_f32 v[222:223], v[222:223], s[28:29], v[224:225] op_sel_hi:[1,0,0] neg_lo:[0,0,1] neg_hi:[0,0,1]
	v_pk_mul_f32 v[224:225], v[208:209], s[26:27] op_sel_hi:[1,0]
	v_mov_b32_e32 v231, v223
	v_pk_fma_f32 v[246:247], v[208:209], s[24:25], v[224:225] op_sel:[0,0,1] op_sel_hi:[1,0,0]
	v_pk_fma_f32 v[208:209], v[208:209], s[24:25], v[224:225] op_sel:[0,0,1] op_sel_hi:[1,0,0] neg_lo:[0,0,1] neg_hi:[0,0,1]
	s_nop 0
	v_mov_b32_e32 v247, v209
	v_pk_mul_f32 v[208:209], v[228:229], s[28:29] op_sel_hi:[1,0]
	s_nop 0
	v_pk_fma_f32 v[224:225], v[228:229], s[28:29], v[208:209] op_sel:[0,0,1] op_sel_hi:[1,0,0]
	v_pk_fma_f32 v[208:209], v[228:229], s[28:29], v[208:209] op_sel_hi:[1,0,0] neg_lo:[0,0,1] neg_hi:[0,0,1]
	s_nop 0
	v_mov_b32_e32 v225, v209
	v_pk_fma_f32 v[208:209], v[220:221], 0, v[220:221] op_sel:[0,0,1] op_sel_hi:[1,0,0]
	v_pk_fma_f32 v[220:221], v[220:221], 0, v[220:221] op_sel:[0,0,1] op_sel_hi:[1,0,0] neg_lo:[0,0,1] neg_hi:[0,0,1]
	s_nop 0
	v_mov_b32_e32 v209, v221
	v_pk_mul_f32 v[220:221], v[204:205], s[30:31] op_sel_hi:[1,0]
	s_nop 0
	v_pk_fma_f32 v[228:229], v[204:205], s[30:31], v[220:221] op_sel:[0,0,1] op_sel_hi:[1,0,0] neg_lo:[0,0,1] neg_hi:[0,0,1]
	v_pk_fma_f32 v[204:205], v[204:205], s[30:31], v[220:221] op_sel_hi:[1,0,0]
	v_pk_mul_f32 v[220:221], v[244:245], s[26:27] op_sel_hi:[1,0]
	v_mov_b32_e32 v229, v205
	v_pk_fma_f32 v[248:249], v[244:245], s[24:25], v[220:221] op_sel:[0,0,1] op_sel_hi:[1,0,0]
	v_pk_fma_f32 v[220:221], v[244:245], s[24:25], v[220:221] op_sel:[0,0,1] op_sel_hi:[1,0,0] neg_lo:[0,0,1] neg_hi:[0,0,1]
	v_pk_add_f32 v[204:205], v[200:201], v[228:229]
	v_mov_b32_e32 v249, v221
	v_pk_mul_f32 v[220:221], v[218:219], s[30:31] op_sel_hi:[1,0]
	v_pk_add_f32 v[200:201], v[200:201], v[228:229] neg_lo:[0,1] neg_hi:[0,1]
	v_pk_fma_f32 v[244:245], v[218:219], s[30:31], v[220:221] op_sel:[0,0,1] op_sel_hi:[1,0,0] neg_lo:[0,0,1] neg_hi:[0,0,1]
	v_pk_fma_f32 v[218:219], v[218:219], s[30:31], v[220:221] op_sel_hi:[1,0,0]
	s_nop 0
	v_mov_b32_e32 v245, v219
	v_pk_mul_f32 v[218:219], v[202:203], s[60:61] op_sel:[1,0]
	v_pk_add_f32 v[222:223], v[230:231], v[244:245] neg_lo:[0,1] neg_hi:[0,1]
	v_pk_fma_f32 v[202:203], v[202:203], s[34:35], v[218:219] op_sel_hi:[0,1,1]
	v_pk_add_f32 v[218:219], v[216:217], v[212:213]
	v_pk_add_f32 v[212:213], v[216:217], v[212:213] neg_lo:[0,1] neg_hi:[0,1]
	v_pk_add_f32 v[216:217], v[214:215], v[210:211]
	v_pk_add_f32 v[210:211], v[214:215], v[210:211] neg_lo:[0,1] neg_hi:[0,1]
	s_nop 0
	v_xor_b32_e32 v215, 0x80000000, v210
	v_mov_b32_e32 v214, v211
	v_pk_add_f32 v[210:211], v[218:219], v[216:217]
	v_pk_add_f32 v[220:221], v[212:213], v[214:215]
	v_pk_add_f32 v[216:217], v[218:219], v[216:217] neg_lo:[0,1] neg_hi:[0,1]
	v_pk_add_f32 v[212:213], v[212:213], v[214:215] neg_lo:[0,1] neg_hi:[0,1]
	v_pk_add_f32 v[214:215], v[242:243], v[224:225]
	v_pk_add_f32 v[218:219], v[242:243], v[224:225] neg_lo:[0,1] neg_hi:[0,1]
	v_pk_add_f32 v[224:225], v[226:227], v[248:249]
	v_pk_add_f32 v[226:227], v[226:227], v[248:249] neg_lo:[0,1] neg_hi:[0,1]
	s_nop 0
	v_xor_b32_e32 v243, 0x80000000, v226
	v_mov_b32_e32 v242, v227
	v_pk_add_f32 v[226:227], v[214:215], v[224:225]
	v_pk_add_f32 v[214:215], v[214:215], v[224:225] neg_lo:[0,1] neg_hi:[0,1]
	v_pk_add_f32 v[224:225], v[206:207], v[208:209]
	v_pk_add_f32 v[206:207], v[206:207], v[208:209] neg_lo:[0,1] neg_hi:[0,1]
	v_pk_add_f32 v[208:209], v[230:231], v[244:245]
	v_xor_b32_e32 v231, 0x80000000, v222
	v_mov_b32_e32 v230, v223
	v_pk_add_f32 v[222:223], v[224:225], v[208:209]
	v_pk_add_f32 v[208:209], v[224:225], v[208:209] neg_lo:[0,1] neg_hi:[0,1]
	v_pk_add_f32 v[224:225], v[246:247], v[202:203]
	v_pk_add_f32 v[202:203], v[246:247], v[202:203] neg_lo:[0,1] neg_hi:[0,1]
	v_pk_add_f32 v[248:249], v[218:219], v[242:243]
	v_xor_b32_e32 v229, 0x80000000, v202
	v_mov_b32_e32 v228, v203
	v_pk_add_f32 v[202:203], v[204:205], v[224:225]
	v_pk_add_f32 v[204:205], v[204:205], v[224:225] neg_lo:[0,1] neg_hi:[0,1]
	v_lshlrev_b32_e32 v225, 3, v181
	v_ashrrev_i32_e32 v181, 4, v181
	v_add_u32_e32 v224, 0, v238
	v_lshlrev_b32_e32 v181, 3, v181
	v_add3_u32 v181, v224, v225, v181
	v_pk_add_f32 v[218:219], v[218:219], v[242:243] neg_lo:[0,1] neg_hi:[0,1]
	v_pk_add_f32 v[242:243], v[206:207], v[230:231]
	v_pk_add_f32 v[206:207], v[206:207], v[230:231] neg_lo:[0,1] neg_hi:[0,1]
	v_pk_add_f32 v[230:231], v[200:201], v[228:229]
	v_pk_add_f32 v[200:201], v[200:201], v[228:229] neg_lo:[0,1] neg_hi:[0,1]
	v_add_u32_e32 v224, 0x1800, v181
	v_add_u32_e32 v181, 0x1c00, v181
	ds_write2_b64 v224, v[210:211], v[226:227] offset0:16 offset1:33
	ds_write2_b64 v224, v[222:223], v[202:203] offset0:50 offset1:67
	ds_write2_b64 v224, v[220:221], v[248:249] offset0:84 offset1:101
	ds_write2_b64 v224, v[242:243], v[230:231] offset0:118 offset1:135
	ds_write2_b64 v224, v[216:217], v[214:215] offset0:152 offset1:169
	ds_write2_b64 v224, v[208:209], v[204:205] offset0:186 offset1:203
	ds_write2_b64 v224, v[212:213], v[218:219] offset0:220 offset1:237
	ds_write2_b64 v181, v[206:207], v[200:201] offset0:126 offset1:143
.LBB0_372:
	s_or_b64 exec, exec, s[2:3]
	v_mov_b32_e32 v200, v180
	s_waitcnt lgkmcnt(0)
	s_barrier
	s_nop 0
	v_cmp_gt_i32_e32 vcc, s56, v200
	s_and_saveexec_b64 s[2:3], vcc
	s_cbranch_execz .LBB0_374
	v_ashrrev_i32_e32 v181, 31, v200
	v_add_u32_sdwa v181, v200, v181 dst_sel:DWORD dst_unused:UNUSED_PAD src0_sel:DWORD src1_sel:BYTE_3
	v_ashrrev_i32_e32 v181, 8, v181
	v_mul_i32_i24_e32 v201, 0x100, v181
	v_sub_u32_e32 v200, v200, v201
	v_mul_i32_i24_e32 v181, 0x1100, v181
	v_lshlrev_b32_e32 v237, 3, v200
	v_ashrrev_i32_e32 v200, 4, v200
	v_lshlrev_b32_e32 v181, 3, v181
	v_lshlrev_b32_e32 v252, 3, v200
	v_add_u32_e32 v222, 0, v237
	v_add3_u32 v238, v222, v181, v252
	ds_read_b64 v[200:201], v238 offset:6272
	ds_read_b64 v[202:203], v238 offset:8448
	ds_read_b64 v[204:205], v238 offset:10624
	ds_read_b64 v[206:207], v238 offset:12800
	ds_read_b64 v[208:209], v238 offset:14976
	ds_read_b64 v[210:211], v238 offset:17152
	ds_read_b64 v[212:213], v238 offset:19328
	ds_read_b64 v[214:215], v238 offset:21504
	ds_read_b64 v[216:217], v238 offset:34560
	ds_read_b64 v[218:219], v238 offset:36736
	ds_read_b64 v[220:221], v238 offset:38912
	ds_read_b64 v[222:223], v222
	ds_read_b64 v[224:225], v238 offset:23680
	ds_read_b64 v[226:227], v238 offset:25856
	ds_read_b64 v[228:229], v238 offset:28032
	ds_read_b64 v[230:231], v238 offset:30208
	ds_read_b64 v[238:239], v238 offset:32384
	s_waitcnt lgkmcnt(5)
	v_pk_mul_f32 v[242:243], v[202:203], v[222:223] op_sel:[1,1] op_sel_hi:[1,0]
	s_mov_b32 s61, s34
	v_pk_fma_f32 v[244:245], v[202:203], v[222:223], v[242:243] op_sel_hi:[0,1,1] neg_lo:[0,0,1]
	v_pk_mul_f32 v[202:203], v[222:223], v[222:223] op_sel:[1,1] op_sel_hi:[1,0]
	s_mov_b32 s35, s24
	v_pk_fma_f32 v[242:243], v[222:223], v[222:223], v[202:203] op_sel_hi:[1,0,1] neg_lo:[0,0,1] neg_hi:[0,0,1]
	v_pk_fma_f32 v[202:203], v[222:223], v[222:223], v[202:203] op_sel_hi:[1,0,1]
	v_mov_b32_e32 v246, v242
	v_mov_b32_e32 v247, v203
	v_pk_mul_f32 v[202:203], v[204:205], v[202:203] op_sel:[1,1] op_sel_hi:[0,1]
	v_pk_fma_f32 v[248:249], v[204:205], v[242:243], v[202:203] neg_lo:[0,0,1] neg_hi:[0,0,1]
	v_pk_fma_f32 v[202:203], v[204:205], v[242:243], v[202:203] op_sel_hi:[1,0,1]
	v_pk_mul_f32 v[204:205], v[222:223], v[246:247] op_sel:[1,0] op_sel_hi:[0,1]
	v_mov_b32_e32 v249, v203
	v_pk_mul_f32 v[202:203], v[222:223], v[246:247]
	v_pk_add_f32 v[204:205], v[204:205], v[204:205] op_sel:[0,1] op_sel_hi:[0,1]
	v_pk_mul_f32 v[242:243], v[206:207], v[204:205]
	v_pk_add_f32 v[202:203], v[202:203], v[202:203] op_sel:[0,1] op_sel_hi:[0,1] neg_lo:[0,1] neg_hi:[0,1]
	v_pk_fma_f32 v[246:247], v[206:207], v[202:203], v[242:243] op_sel:[0,0,1] op_sel_hi:[1,1,0] neg_lo:[0,0,1] neg_hi:[0,0,1]
	v_pk_fma_f32 v[206:207], v[206:207], v[202:203], v[242:243] op_sel:[0,0,1] op_sel_hi:[1,1,0]
	v_pk_mul_f32 v[204:205], v[222:223], v[204:205]
	v_mov_b32_e32 v247, v207
	v_pk_fma_f32 v[206:207], v[222:223], v[202:203], v[204:205] op_sel:[0,0,1] op_sel_hi:[1,1,0] neg_lo:[0,0,1] neg_hi:[0,0,1]
	v_pk_fma_f32 v[202:203], v[222:223], v[202:203], v[204:205] op_sel:[0,0,1] op_sel_hi:[1,1,0]
	v_mov_b32_e32 v204, v206
	v_mov_b32_e32 v205, v203
	v_pk_mul_f32 v[202:203], v[208:209], v[202:203] op_sel:[1,1] op_sel_hi:[0,1]
	v_pk_fma_f32 v[242:243], v[208:209], v[206:207], v[202:203] neg_lo:[0,0,1] neg_hi:[0,0,1]
	v_pk_fma_f32 v[202:203], v[208:209], v[206:207], v[202:203] op_sel_hi:[1,0,1]
	v_add_u32_e32 v181, s57, v181
	v_mov_b32_e32 v243, v203
	v_pk_mul_f32 v[202:203], v[222:223], v[204:205]
	v_pk_mul_f32 v[204:205], v[222:223], v[204:205] op_sel:[1,0] op_sel_hi:[0,1]
	v_pk_add_f32 v[204:205], v[204:205], v[204:205] op_sel:[0,1] op_sel_hi:[0,1]
	v_pk_mul_f32 v[206:207], v[210:211], v[204:205]
	v_pk_add_f32 v[202:203], v[202:203], v[202:203] op_sel:[0,1] op_sel_hi:[0,1] neg_lo:[0,1] neg_hi:[0,1]
	v_pk_fma_f32 v[208:209], v[210:211], v[202:203], v[206:207] op_sel:[0,0,1] op_sel_hi:[1,1,0] neg_lo:[0,0,1] neg_hi:[0,0,1]
	v_pk_fma_f32 v[206:207], v[210:211], v[202:203], v[206:207] op_sel:[0,0,1] op_sel_hi:[1,1,0]
	v_pk_mul_f32 v[204:205], v[222:223], v[204:205]
	v_mov_b32_e32 v209, v207
	v_pk_fma_f32 v[206:207], v[222:223], v[202:203], v[204:205] op_sel:[0,0,1] op_sel_hi:[1,1,0] neg_lo:[0,0,1] neg_hi:[0,0,1]
	v_pk_fma_f32 v[202:203], v[222:223], v[202:203], v[204:205] op_sel:[0,0,1] op_sel_hi:[1,1,0]
	v_mov_b32_e32 v204, v206
	v_mov_b32_e32 v205, v203
	v_pk_mul_f32 v[202:203], v[212:213], v[202:203] op_sel:[1,1] op_sel_hi:[0,1]
	v_pk_fma_f32 v[210:211], v[212:213], v[206:207], v[202:203] neg_lo:[0,0,1] neg_hi:[0,0,1]
	v_pk_fma_f32 v[202:203], v[212:213], v[206:207], v[202:203] op_sel_hi:[1,0,1]
	v_add3_u32 v181, v181, v237, v252
	v_mov_b32_e32 v211, v203
	v_pk_mul_f32 v[202:203], v[222:223], v[204:205]
	v_pk_mul_f32 v[204:205], v[222:223], v[204:205] op_sel:[1,0] op_sel_hi:[0,1]
	v_pk_add_f32 v[204:205], v[204:205], v[204:205] op_sel:[0,1] op_sel_hi:[0,1]
	v_pk_mul_f32 v[206:207], v[214:215], v[204:205]
	v_pk_add_f32 v[202:203], v[202:203], v[202:203] op_sel:[0,1] op_sel_hi:[0,1] neg_lo:[0,1] neg_hi:[0,1]
	v_pk_fma_f32 v[212:213], v[214:215], v[202:203], v[206:207] op_sel:[0,0,1] op_sel_hi:[1,1,0] neg_lo:[0,0,1] neg_hi:[0,0,1]
	v_pk_fma_f32 v[206:207], v[214:215], v[202:203], v[206:207] op_sel:[0,0,1] op_sel_hi:[1,1,0]
	v_pk_mul_f32 v[204:205], v[222:223], v[204:205]
	v_mov_b32_e32 v213, v207
	v_pk_fma_f32 v[206:207], v[222:223], v[202:203], v[204:205] op_sel:[0,0,1] op_sel_hi:[1,1,0] neg_lo:[0,0,1] neg_hi:[0,0,1]
	v_pk_fma_f32 v[202:203], v[222:223], v[202:203], v[204:205] op_sel:[0,0,1] op_sel_hi:[1,1,0]
	v_mov_b32_e32 v204, v206
	v_mov_b32_e32 v205, v203
	s_waitcnt lgkmcnt(4)
	v_pk_mul_f32 v[202:203], v[224:225], v[202:203] op_sel:[1,1] op_sel_hi:[0,1]
	v_pk_fma_f32 v[214:215], v[224:225], v[206:207], v[202:203] neg_lo:[0,0,1] neg_hi:[0,0,1]
	v_pk_fma_f32 v[202:203], v[224:225], v[206:207], v[202:203] op_sel_hi:[1,0,1]
	s_nop 0
	v_mov_b32_e32 v215, v203
	v_pk_mul_f32 v[202:203], v[222:223], v[204:205]
	v_pk_mul_f32 v[204:205], v[222:223], v[204:205] op_sel:[1,0] op_sel_hi:[0,1]
	v_pk_add_f32 v[204:205], v[204:205], v[204:205] op_sel:[0,1] op_sel_hi:[0,1]
	s_waitcnt lgkmcnt(3)
	v_pk_mul_f32 v[206:207], v[226:227], v[204:205]
	v_pk_add_f32 v[202:203], v[202:203], v[202:203] op_sel:[0,1] op_sel_hi:[0,1] neg_lo:[0,1] neg_hi:[0,1]
	v_pk_fma_f32 v[224:225], v[226:227], v[202:203], v[206:207] op_sel:[0,0,1] op_sel_hi:[1,1,0] neg_lo:[0,0,1] neg_hi:[0,0,1]
	v_pk_fma_f32 v[206:207], v[226:227], v[202:203], v[206:207] op_sel:[0,0,1] op_sel_hi:[1,1,0]
	v_pk_mul_f32 v[204:205], v[222:223], v[204:205]
	v_mov_b32_e32 v225, v207
	v_pk_fma_f32 v[206:207], v[222:223], v[202:203], v[204:205] op_sel:[0,0,1] op_sel_hi:[1,1,0] neg_lo:[0,0,1] neg_hi:[0,0,1]
	v_pk_fma_f32 v[202:203], v[222:223], v[202:203], v[204:205] op_sel:[0,0,1] op_sel_hi:[1,1,0]
	v_mov_b32_e32 v204, v206
	v_mov_b32_e32 v205, v203
	s_waitcnt lgkmcnt(2)
	v_pk_mul_f32 v[202:203], v[228:229], v[202:203] op_sel:[1,1] op_sel_hi:[0,1]
	v_pk_fma_f32 v[226:227], v[228:229], v[206:207], v[202:203] neg_lo:[0,0,1] neg_hi:[0,0,1]
	v_pk_fma_f32 v[202:203], v[228:229], v[206:207], v[202:203] op_sel_hi:[1,0,1]
	s_nop 0
	v_mov_b32_e32 v227, v203
	v_pk_mul_f32 v[202:203], v[222:223], v[204:205]
	v_pk_mul_f32 v[204:205], v[222:223], v[204:205] op_sel:[1,0] op_sel_hi:[0,1]
	v_pk_add_f32 v[204:205], v[204:205], v[204:205] op_sel:[0,1] op_sel_hi:[0,1]
	s_waitcnt lgkmcnt(1)
	v_pk_mul_f32 v[206:207], v[230:231], v[204:205]
	v_pk_add_f32 v[202:203], v[202:203], v[202:203] op_sel:[0,1] op_sel_hi:[0,1] neg_lo:[0,1] neg_hi:[0,1]
	v_pk_fma_f32 v[228:229], v[230:231], v[202:203], v[206:207] op_sel:[0,0,1] op_sel_hi:[1,1,0] neg_lo:[0,0,1] neg_hi:[0,0,1]
	v_pk_fma_f32 v[206:207], v[230:231], v[202:203], v[206:207] op_sel:[0,0,1] op_sel_hi:[1,1,0]
	v_pk_mul_f32 v[204:205], v[222:223], v[204:205]
	v_mov_b32_e32 v229, v207
	v_pk_fma_f32 v[206:207], v[222:223], v[202:203], v[204:205] op_sel:[0,0,1] op_sel_hi:[1,1,0] neg_lo:[0,0,1] neg_hi:[0,0,1]
	v_pk_fma_f32 v[202:203], v[222:223], v[202:203], v[204:205] op_sel:[0,0,1] op_sel_hi:[1,1,0]
	v_mov_b32_e32 v204, v206
	v_mov_b32_e32 v205, v203
	s_waitcnt lgkmcnt(0)
	v_pk_mul_f32 v[202:203], v[238:239], v[202:203] op_sel:[1,1] op_sel_hi:[0,1]
	v_pk_fma_f32 v[230:231], v[238:239], v[206:207], v[202:203] neg_lo:[0,0,1] neg_hi:[0,0,1]
	v_pk_fma_f32 v[202:203], v[238:239], v[206:207], v[202:203] op_sel_hi:[1,0,1]
	s_nop 0
	v_mov_b32_e32 v231, v203
	v_pk_mul_f32 v[202:203], v[222:223], v[204:205]
	v_pk_mul_f32 v[204:205], v[222:223], v[204:205] op_sel:[1,0] op_sel_hi:[0,1]
	v_pk_add_f32 v[204:205], v[204:205], v[204:205] op_sel:[0,1] op_sel_hi:[0,1]
	v_pk_mul_f32 v[206:207], v[216:217], v[204:205]
	v_pk_add_f32 v[202:203], v[202:203], v[202:203] op_sel:[0,1] op_sel_hi:[0,1] neg_lo:[0,1] neg_hi:[0,1]
	v_pk_fma_f32 v[238:239], v[216:217], v[202:203], v[206:207] op_sel:[0,0,1] op_sel_hi:[1,1,0] neg_lo:[0,0,1] neg_hi:[0,0,1]
	v_pk_fma_f32 v[206:207], v[216:217], v[202:203], v[206:207] op_sel:[0,0,1] op_sel_hi:[1,1,0]
	v_pk_mul_f32 v[202:203], v[222:223], v[202:203]
	v_mov_b32_e32 v239, v207
	v_pk_fma_f32 v[206:207], v[222:223], v[204:205], v[202:203] op_sel:[0,0,1] op_sel_hi:[1,1,0] neg_lo:[1,0,0] neg_hi:[1,0,0]
	v_pk_fma_f32 v[202:203], v[222:223], v[204:205], v[202:203] op_sel:[0,0,1] op_sel_hi:[1,1,0]
	v_mov_b32_e32 v205, v207
	v_mov_b32_e32 v204, v202
	v_pk_mul_f32 v[216:217], v[218:219], v[202:203] op_sel:[1,0] op_sel_hi:[0,0]
	v_pk_mov_b32 v[202:203], v[206:207], v[202:203] op_sel:[1,0]
	v_pk_mul_f32 v[204:205], v[222:223], v[204:205]
	v_pk_mul_f32 v[202:203], v[222:223], v[202:203]
	v_pk_add_f32 v[204:205], v[204:205], v[204:205] op_sel:[1,0] op_sel_hi:[1,0]
	v_pk_fma_f32 v[250:251], v[218:219], v[206:207], v[216:217] op_sel:[0,1,0] neg_lo:[0,0,1] neg_hi:[0,0,1]
	v_pk_fma_f32 v[206:207], v[218:219], v[206:207], v[216:217] op_sel:[0,1,0]
	v_pk_mul_f32 v[204:205], v[220:221], v[204:205] op_sel:[1,0] op_sel_hi:[0,1]
	v_pk_add_f32 v[202:203], v[202:203], v[202:203] op_sel:[0,1] op_sel_hi:[0,1] neg_lo:[0,1] neg_hi:[0,1]
	v_mov_b32_e32 v251, v207
	v_pk_fma_f32 v[206:207], v[220:221], v[202:203], v[204:205] neg_lo:[0,0,1] neg_hi:[0,0,1]
	v_pk_fma_f32 v[202:203], v[220:221], v[202:203], v[204:205]
	v_pk_add_f32 v[204:205], v[242:243], v[230:231]
	v_mov_b32_e32 v207, v203
	v_pk_add_f32 v[202:203], v[200:201], v[214:215]
	v_pk_add_f32 v[200:201], v[200:201], v[214:215] neg_lo:[0,1] neg_hi:[0,1]
	v_pk_add_f32 v[214:215], v[242:243], v[230:231] neg_lo:[0,1] neg_hi:[0,1]
	v_pk_add_f32 v[220:221], v[208:209], v[238:239]
	v_xor_b32_e32 v217, 0x80000000, v214
	v_mov_b32_e32 v216, v215
	v_pk_add_f32 v[208:209], v[208:209], v[238:239] neg_lo:[0,1] neg_hi:[0,1]
	v_pk_add_f32 v[214:215], v[202:203], v[204:205]
	v_pk_add_f32 v[218:219], v[200:201], v[216:217]
	v_pk_add_f32 v[202:203], v[202:203], v[204:205] neg_lo:[0,1] neg_hi:[0,1]
	v_pk_add_f32 v[200:201], v[200:201], v[216:217] neg_lo:[0,1] neg_hi:[0,1]
	v_pk_add_f32 v[204:205], v[244:245], v[224:225]
	v_pk_add_f32 v[216:217], v[244:245], v[224:225] neg_lo:[0,1] neg_hi:[0,1]
	v_xor_b32_e32 v223, 0x80000000, v208
	v_mov_b32_e32 v222, v209
	v_pk_add_f32 v[208:209], v[204:205], v[220:221]
	v_pk_add_f32 v[224:225], v[216:217], v[222:223]
	v_pk_add_f32 v[204:205], v[204:205], v[220:221] neg_lo:[0,1] neg_hi:[0,1]
	v_pk_add_f32 v[216:217], v[216:217], v[222:223] neg_lo:[0,1] neg_hi:[0,1]
	v_pk_add_f32 v[220:221], v[248:249], v[226:227]
	v_pk_add_f32 v[222:223], v[248:249], v[226:227] neg_lo:[0,1] neg_hi:[0,1]
	v_pk_add_f32 v[226:227], v[210:211], v[250:251]
	v_pk_add_f32 v[210:211], v[210:211], v[250:251] neg_lo:[0,1] neg_hi:[0,1]
	s_nop 0
	v_xor_b32_e32 v231, 0x80000000, v210
	v_mov_b32_e32 v230, v211
	v_pk_add_f32 v[238:239], v[222:223], v[230:231]
	v_pk_add_f32 v[222:223], v[222:223], v[230:231] neg_lo:[0,1] neg_hi:[0,1]
	v_pk_add_f32 v[230:231], v[212:213], v[206:207]
	v_pk_add_f32 v[206:207], v[212:213], v[206:207] neg_lo:[0,1] neg_hi:[0,1]
	v_pk_add_f32 v[210:211], v[220:221], v[226:227]
	v_pk_add_f32 v[220:221], v[220:221], v[226:227] neg_lo:[0,1] neg_hi:[0,1]
	v_pk_add_f32 v[226:227], v[246:247], v[228:229]
	v_pk_add_f32 v[228:229], v[246:247], v[228:229] neg_lo:[0,1] neg_hi:[0,1]
	v_xor_b32_e32 v213, 0x80000000, v206
	v_mov_b32_e32 v212, v207
	v_pk_add_f32 v[242:243], v[228:229], v[212:213]
	v_pk_add_f32 v[212:213], v[228:229], v[212:213] neg_lo:[0,1] neg_hi:[0,1]
	v_pk_mul_f32 v[228:229], v[224:225], s[24:25] op_sel_hi:[1,0]
	v_pk_add_f32 v[206:207], v[226:227], v[230:231]
	v_pk_add_f32 v[226:227], v[226:227], v[230:231] neg_lo:[0,1] neg_hi:[0,1]
	v_pk_fma_f32 v[230:231], v[224:225], s[26:27], v[228:229] op_sel:[0,0,1] op_sel_hi:[1,0,0]
	v_pk_fma_f32 v[224:225], v[224:225], s[26:27], v[228:229] op_sel:[0,0,1] op_sel_hi:[1,0,0] neg_lo:[0,0,1] neg_hi:[0,0,1]
	s_nop 0
	v_mov_b32_e32 v231, v225
	v_pk_mul_f32 v[224:225], v[204:205], s[28:29] op_sel_hi:[1,0]
	s_nop 0
	v_pk_fma_f32 v[228:229], v[204:205], s[28:29], v[224:225] op_sel:[0,0,1] op_sel_hi:[1,0,0]
	v_pk_fma_f32 v[204:205], v[204:205], s[28:29], v[224:225] op_sel_hi:[1,0,0] neg_lo:[0,0,1] neg_hi:[0,0,1]
	v_pk_mul_f32 v[224:225], v[216:217], s[26:27] op_sel_hi:[1,0]
	v_mov_b32_e32 v229, v205
	v_pk_fma_f32 v[244:245], v[216:217], s[24:25], v[224:225] op_sel:[0,0,1] op_sel_hi:[1,0,0]
	v_pk_fma_f32 v[216:217], v[216:217], s[24:25], v[224:225] op_sel:[0,0,1] op_sel_hi:[1,0,0] neg_lo:[0,0,1] neg_hi:[0,0,1]
	s_nop 0
	v_mov_b32_e32 v245, v217
	v_pk_mul_f32 v[216:217], v[238:239], s[28:29] op_sel_hi:[1,0]
	s_nop 0
	v_pk_fma_f32 v[224:225], v[238:239], s[28:29], v[216:217] op_sel:[0,0,1] op_sel_hi:[1,0,0]
	v_pk_fma_f32 v[216:217], v[238:239], s[28:29], v[216:217] op_sel_hi:[1,0,0] neg_lo:[0,0,1] neg_hi:[0,0,1]
	s_nop 0
	v_mov_b32_e32 v225, v217
	v_pk_fma_f32 v[216:217], v[220:221], 0, v[220:221] op_sel:[0,0,1] op_sel_hi:[1,0,0]
	v_pk_fma_f32 v[220:221], v[220:221], 0, v[220:221] op_sel:[0,0,1] op_sel_hi:[1,0,0] neg_lo:[0,0,1] neg_hi:[0,0,1]
	s_nop 0
	v_mov_b32_e32 v217, v221
	v_pk_mul_f32 v[220:221], v[222:223], s[30:31] op_sel_hi:[1,0]
	s_nop 0
	v_pk_fma_f32 v[238:239], v[222:223], s[30:31], v[220:221] op_sel:[0,0,1] op_sel_hi:[1,0,0] neg_lo:[0,0,1] neg_hi:[0,0,1]
	v_pk_fma_f32 v[220:221], v[222:223], s[30:31], v[220:221] op_sel_hi:[1,0,0]
	v_pk_mul_f32 v[222:223], v[242:243], s[26:27] op_sel_hi:[1,0]
	v_mov_b32_e32 v239, v221
	v_pk_fma_f32 v[246:247], v[242:243], s[24:25], v[222:223] op_sel:[0,0,1] op_sel_hi:[1,0,0]
	v_pk_fma_f32 v[222:223], v[242:243], s[24:25], v[222:223] op_sel:[0,0,1] op_sel_hi:[1,0,0] neg_lo:[0,0,1] neg_hi:[0,0,1]
	v_pk_add_f32 v[220:221], v[200:201], v[238:239]
	v_mov_b32_e32 v247, v223
	v_pk_mul_f32 v[222:223], v[226:227], s[30:31] op_sel_hi:[1,0]
	v_pk_add_f32 v[200:201], v[200:201], v[238:239] neg_lo:[0,1] neg_hi:[0,1]
	v_pk_fma_f32 v[242:243], v[226:227], s[30:31], v[222:223] op_sel:[0,0,1] op_sel_hi:[1,0,0] neg_lo:[0,0,1] neg_hi:[0,0,1]
	v_pk_fma_f32 v[222:223], v[226:227], s[30:31], v[222:223] op_sel_hi:[1,0,0]
	s_nop 0
	v_mov_b32_e32 v243, v223
	v_pk_mul_f32 v[222:223], v[212:213], s[60:61] op_sel:[1,0]
	v_pk_add_f32 v[204:205], v[228:229], v[242:243]
	v_pk_fma_f32 v[212:213], v[212:213], s[34:35], v[222:223] op_sel_hi:[0,1,1]
	v_pk_add_f32 v[222:223], v[214:215], v[210:211]
	v_pk_add_f32 v[210:211], v[214:215], v[210:211] neg_lo:[0,1] neg_hi:[0,1]
	v_pk_add_f32 v[214:215], v[208:209], v[206:207]
	v_pk_add_f32 v[206:207], v[208:209], v[206:207] neg_lo:[0,1] neg_hi:[0,1]
	s_nop 0
	v_xor_b32_e32 v209, 0x80000000, v206
	v_mov_b32_e32 v208, v207
	v_pk_add_f32 v[206:207], v[222:223], v[214:215]
	v_pk_add_f32 v[226:227], v[210:211], v[208:209]
	v_pk_add_f32 v[214:215], v[222:223], v[214:215] neg_lo:[0,1] neg_hi:[0,1]
	v_pk_add_f32 v[208:209], v[210:211], v[208:209] neg_lo:[0,1] neg_hi:[0,1]
	v_pk_add_f32 v[210:211], v[218:219], v[224:225]
	v_pk_add_f32 v[218:219], v[218:219], v[224:225] neg_lo:[0,1] neg_hi:[0,1]
	v_pk_add_f32 v[222:223], v[230:231], v[246:247]
	v_pk_add_f32 v[224:225], v[230:231], v[246:247] neg_lo:[0,1] neg_hi:[0,1]
	s_nop 0
	v_xor_b32_e32 v231, 0x80000000, v224
	v_mov_b32_e32 v230, v225
	v_pk_add_f32 v[224:225], v[210:211], v[222:223]
	v_pk_add_f32 v[210:211], v[210:211], v[222:223] neg_lo:[0,1] neg_hi:[0,1]
	v_pk_add_f32 v[222:223], v[202:203], v[216:217]
	v_pk_add_f32 v[202:203], v[202:203], v[216:217] neg_lo:[0,1] neg_hi:[0,1]
	v_pk_add_f32 v[216:217], v[228:229], v[242:243] neg_lo:[0,1] neg_hi:[0,1]
	v_pk_add_f32 v[246:247], v[218:219], v[230:231]
	v_xor_b32_e32 v229, 0x80000000, v216
	v_mov_b32_e32 v228, v217
	v_pk_add_f32 v[216:217], v[222:223], v[204:205]
	v_pk_add_f32 v[204:205], v[222:223], v[204:205] neg_lo:[0,1] neg_hi:[0,1]
	v_pk_add_f32 v[222:223], v[244:245], v[212:213]
	v_pk_add_f32 v[212:213], v[244:245], v[212:213] neg_lo:[0,1] neg_hi:[0,1]
	v_pk_add_f32 v[218:219], v[218:219], v[230:231] neg_lo:[0,1] neg_hi:[0,1]
	v_pk_add_f32 v[230:231], v[202:203], v[228:229]
	v_pk_add_f32 v[202:203], v[202:203], v[228:229] neg_lo:[0,1] neg_hi:[0,1]
	v_xor_b32_e32 v229, 0x80000000, v212
	v_mov_b32_e32 v228, v213
	v_pk_add_f32 v[212:213], v[220:221], v[222:223]
	v_pk_add_f32 v[238:239], v[200:201], v[228:229]
	v_pk_add_f32 v[220:221], v[220:221], v[222:223] neg_lo:[0,1] neg_hi:[0,1]
	v_pk_add_f32 v[200:201], v[200:201], v[228:229] neg_lo:[0,1] neg_hi:[0,1]
	ds_write_b64 v181, v[206:207]
	ds_write_b64 v181, v[224:225] offset:2176
	ds_write_b64 v181, v[216:217] offset:4352
	ds_write_b64 v181, v[212:213] offset:6528
	ds_write_b64 v181, v[226:227] offset:8704
	ds_write_b64 v181, v[246:247] offset:10880
	ds_write_b64 v181, v[230:231] offset:13056
	ds_write_b64 v181, v[238:239] offset:15232
	ds_write_b64 v181, v[214:215] offset:17408
	ds_write_b64 v181, v[210:211] offset:19584
	ds_write_b64 v181, v[204:205] offset:21760
	ds_write_b64 v181, v[220:221] offset:23936
	ds_write_b64 v181, v[208:209] offset:26112
	ds_write_b64 v181, v[218:219] offset:28288
	ds_write_b64 v181, v[202:203] offset:30464
	ds_write_b64 v181, v[200:201] offset:32640

.LBB0_487:
	s_or_b64 exec, exec, s[2:3]
	v_mov_b32_e32 v0, v180
	s_waitcnt lgkmcnt(0)
	s_barrier
	s_nop 0
	v_cmp_gt_i32_e32 vcc, s16, v0
	s_and_saveexec_b64 s[2:3], vcc
	s_cbranch_execz .LBB0_489
	v_ashrrev_i32_e32 v1, 31, v0
	v_lshrrev_b32_e32 v1, 27, v1
	v_add_u32_e32 v1, v0, v1
	v_lshrrev_b32_e32 v2, 5, v1
	v_and_b32_e32 v1, 0xffffffe0, v1
	v_sub_u32_e32 v0, v0, v1
	v_lshrrev_b16_sdwa v1, v175, sext(v0) dst_sel:DWORD dst_unused:UNUSED_PAD src0_sel:DWORD src1_sel:BYTE_0
	v_and_b32_e32 v1, 15, v1
	v_add_u16_e32 v1, v0, v1
	v_ashrrev_i16_sdwa v8, v176, sext(v1) dst_sel:DWORD dst_unused:UNUSED_PAD src0_sel:DWORD src1_sel:BYTE_0
	v_and_b32_e32 v1, 0xf0, v1
	v_sub_u16_e32 v54, v0, v1
	v_mul_lo_u32 v91, v2, s17
	v_lshlrev_b32_e32 v2, 3, v0
	v_ashrrev_i32_e32 v0, 4, v0
	v_add_u32_e32 v1, s18, v91
	v_lshlrev_b32_e32 v0, 3, v0
	v_bfe_i32 v106, v54, 0, 8
	v_add3_u32 v4, v1, v2, v0
	v_mad_i32_i24 v107, v106, s19, 0
	ds_read2_b64 v[0:3], v4 offset1:34
	ds_read2_b64 v[58:61], v4 offset0:68 offset1:102
	ds_read2_b64 v[70:73], v4 offset0:136 offset1:170
	ds_read2_b64 v[74:77], v4 offset0:204 offset1:238
	v_add_u32_e32 v4, 0x800, v4
	v_add_u32_e32 v54, 0x808, v107
	ds_read2_b64 v[84:87], v4 offset0:16 offset1:50
	ds_read2_b64 v[108:111], v4 offset0:84 offset1:118
	ds_read2_b64 v[112:115], v4 offset0:152 offset1:186
	ds_read2_b64 v[4:7], v4 offset0:220 offset1:254
	ds_read2_b64 v[62:65], v54 offset1:1
	s_mov_b32 s31, s28
	s_mov_b32 s29, s14
	v_bfe_i32 v8, v8, 0, 16
	v_lshl_add_u32 v8, v8, 8, v106
	s_waitcnt lgkmcnt(0)
	v_pk_mul_f32 v[54:55], v[2:3], v[62:63] op_sel:[1,1] op_sel_hi:[1,0]
	s_nop 0
	v_pk_fma_f32 v[56:57], v[2:3], v[62:63], v[54:55] op_sel_hi:[0,1,1] neg_lo:[0,0,1]
	v_pk_mul_f32 v[2:3], v[58:59], v[64:65] op_sel:[1,1] op_sel_hi:[1,0]
	s_nop 0
	v_pk_fma_f32 v[54:55], v[58:59], v[64:65], v[2:3] neg_lo:[0,0,1] neg_hi:[0,0,1]
	v_pk_fma_f32 v[2:3], v[58:59], v[64:65], v[2:3] op_sel_hi:[0,1,1]
	v_add_u32_e32 v2, 0x818, v107
	ds_read2_b64 v[64:67], v2 offset1:1
	v_mov_b32_e32 v55, v3
	s_waitcnt lgkmcnt(0)
	v_pk_mul_f32 v[58:59], v[60:61], v[64:65] op_sel:[1,1] op_sel_hi:[1,0]
	s_nop 0
	v_pk_fma_f32 v[2:3], v[60:61], v[64:65], v[58:59] op_sel_hi:[0,1,1] neg_lo:[0,0,1]
	v_pk_mul_f32 v[58:59], v[70:71], v[66:67] op_sel:[1,1] op_sel_hi:[1,0]
	s_nop 0
	v_pk_fma_f32 v[64:65], v[70:71], v[66:67], v[58:59] neg_lo:[0,0,1] neg_hi:[0,0,1]
	v_pk_fma_f32 v[58:59], v[70:71], v[66:67], v[58:59] op_sel_hi:[0,1,1]
	v_add_u32_e32 v58, 0x828, v107
	ds_read2_b64 v[116:119], v58 offset1:1
	v_mov_b32_e32 v65, v59
	s_waitcnt lgkmcnt(0)
	v_pk_mul_f32 v[58:59], v[72:73], v[116:117] op_sel:[1,1] op_sel_hi:[1,0]
	s_nop 0
	v_pk_fma_f32 v[62:63], v[72:73], v[116:117], v[58:59] op_sel_hi:[0,1,1] neg_lo:[0,0,1]
	v_pk_mul_f32 v[58:59], v[74:75], v[118:119] op_sel:[1,1] op_sel_hi:[1,0]
	s_nop 0
	v_pk_fma_f32 v[60:61], v[74:75], v[118:119], v[58:59] neg_lo:[0,0,1] neg_hi:[0,0,1]
	v_pk_fma_f32 v[58:59], v[74:75], v[118:119], v[58:59] op_sel_hi:[0,1,1]
	v_add_u32_e32 v58, 0x838, v107
	ds_read2_b64 v[70:73], v58 offset1:1
	v_mov_b32_e32 v61, v59
	s_waitcnt lgkmcnt(0)
	v_pk_mul_f32 v[66:67], v[76:77], v[70:71] op_sel:[1,1] op_sel_hi:[1,0]
	s_nop 0
	v_pk_fma_f32 v[58:59], v[76:77], v[70:71], v[66:67] op_sel_hi:[0,1,1] neg_lo:[0,0,1]
	v_pk_mul_f32 v[66:67], v[84:85], v[72:73] op_sel:[1,1] op_sel_hi:[1,0]
	s_nop 0
	v_pk_fma_f32 v[74:75], v[84:85], v[72:73], v[66:67] neg_lo:[0,0,1] neg_hi:[0,0,1]
	v_pk_fma_f32 v[66:67], v[84:85], v[72:73], v[66:67] op_sel_hi:[0,1,1]
	v_add_u32_e32 v66, 0x848, v107
	ds_read2_b64 v[116:119], v66 offset1:1
	v_mov_b32_e32 v75, v67
	s_waitcnt lgkmcnt(0)
	v_pk_mul_f32 v[66:67], v[86:87], v[116:117] op_sel:[1,1] op_sel_hi:[1,0]
	s_nop 0
	v_pk_fma_f32 v[72:73], v[86:87], v[116:117], v[66:67] op_sel_hi:[0,1,1] neg_lo:[0,0,1]
	v_pk_mul_f32 v[66:67], v[108:109], v[118:119] op_sel:[1,1] op_sel_hi:[1,0]
	s_nop 0
	v_pk_fma_f32 v[70:71], v[108:109], v[118:119], v[66:67] neg_lo:[0,0,1] neg_hi:[0,0,1]
	v_pk_fma_f32 v[66:67], v[108:109], v[118:119], v[66:67] op_sel_hi:[0,1,1]
	v_add_u32_e32 v66, 0x858, v107
	ds_read2_b64 v[116:119], v66 offset1:1
	v_mov_b32_e32 v71, v67
	s_waitcnt lgkmcnt(0)
	v_pk_mul_f32 v[76:77], v[110:111], v[116:117] op_sel:[1,1] op_sel_hi:[1,0]
	s_nop 0
	v_pk_fma_f32 v[66:67], v[110:111], v[116:117], v[76:77] op_sel_hi:[0,1,1] neg_lo:[0,0,1]
	v_pk_mul_f32 v[76:77], v[112:113], v[118:119] op_sel:[1,1] op_sel_hi:[1,0]
	s_nop 0
	v_pk_fma_f32 v[86:87], v[112:113], v[118:119], v[76:77] neg_lo:[0,0,1] neg_hi:[0,0,1]
	v_pk_fma_f32 v[76:77], v[112:113], v[118:119], v[76:77] op_sel_hi:[0,1,1]
	v_add_u32_e32 v76, 0x868, v107
	ds_read2_b64 v[108:111], v76 offset1:1
	v_mov_b32_e32 v87, v77
	s_waitcnt lgkmcnt(0)
	v_pk_mul_f32 v[76:77], v[114:115], v[108:109] op_sel:[1,1] op_sel_hi:[1,0]
	s_nop 0
	v_pk_fma_f32 v[84:85], v[114:115], v[108:109], v[76:77] op_sel_hi:[0,1,1] neg_lo:[0,0,1]
	v_pk_mul_f32 v[108:109], v[4:5], v[110:111] op_sel:[1,1] op_sel_hi:[1,0]
	v_pk_fma_f32 v[76:77], v[4:5], v[110:111], v[108:109] op_sel_hi:[0,1,1] neg_lo:[0,0,1]
	ds_read_b64 v[4:5], v107 offset:2168
	s_waitcnt lgkmcnt(0)
	v_pk_mul_f32 v[108:109], v[6:7], v[4:5] op_sel:[1,1] op_sel_hi:[1,0]
	s_nop 0
	v_pk_fma_f32 v[110:111], v[6:7], v[4:5], v[108:109] op_sel_hi:[0,1,1] neg_lo:[0,0,1]
	v_pk_add_f32 v[4:5], v[0:1], v[74:75]
	v_pk_add_f32 v[6:7], v[64:65], v[86:87]
	v_pk_add_f32 v[64:65], v[64:65], v[86:87] neg_lo:[0,1] neg_hi:[0,1]
	v_pk_add_f32 v[0:1], v[0:1], v[74:75] neg_lo:[0,1] neg_hi:[0,1]
	v_xor_b32_e32 v75, 0x80000000, v64
	v_mov_b32_e32 v74, v65
	v_pk_add_f32 v[64:65], v[4:5], v[6:7]
	v_pk_add_f32 v[4:5], v[4:5], v[6:7] neg_lo:[0,1] neg_hi:[0,1]
	v_pk_add_f32 v[6:7], v[56:57], v[72:73]
	v_pk_add_f32 v[56:57], v[56:57], v[72:73] neg_lo:[0,1] neg_hi:[0,1]
	v_pk_add_f32 v[72:73], v[62:63], v[84:85]
	v_pk_add_f32 v[62:63], v[62:63], v[84:85] neg_lo:[0,1] neg_hi:[0,1]
	v_pk_add_f32 v[86:87], v[0:1], v[74:75]
	v_pk_add_f32 v[0:1], v[0:1], v[74:75] neg_lo:[0,1] neg_hi:[0,1]
	v_xor_b32_e32 v75, 0x80000000, v62
	v_mov_b32_e32 v74, v63
	v_pk_add_f32 v[62:63], v[6:7], v[72:73]
	v_pk_add_f32 v[6:7], v[6:7], v[72:73] neg_lo:[0,1] neg_hi:[0,1]
	v_pk_add_f32 v[72:73], v[54:55], v[70:71]
	v_pk_add_f32 v[54:55], v[54:55], v[70:71] neg_lo:[0,1] neg_hi:[0,1]
	v_pk_add_f32 v[70:71], v[60:61], v[76:77]
	v_pk_add_f32 v[60:61], v[60:61], v[76:77] neg_lo:[0,1] neg_hi:[0,1]
	v_pk_add_f32 v[84:85], v[56:57], v[74:75]
	v_pk_add_f32 v[56:57], v[56:57], v[74:75] neg_lo:[0,1] neg_hi:[0,1]
	v_xor_b32_e32 v75, 0x80000000, v60
	v_mov_b32_e32 v74, v61
	v_pk_add_f32 v[60:61], v[72:73], v[70:71]
	v_pk_add_f32 v[70:71], v[72:73], v[70:71] neg_lo:[0,1] neg_hi:[0,1]
	v_pk_add_f32 v[72:73], v[2:3], v[66:67]
	v_pk_add_f32 v[2:3], v[2:3], v[66:67] neg_lo:[0,1] neg_hi:[0,1]
	v_pk_add_f32 v[66:67], v[58:59], v[110:111]
	v_pk_add_f32 v[58:59], v[58:59], v[110:111] neg_lo:[0,1] neg_hi:[0,1]
	v_pk_add_f32 v[76:77], v[54:55], v[74:75]
	v_pk_add_f32 v[54:55], v[54:55], v[74:75] neg_lo:[0,1] neg_hi:[0,1]
	v_xor_b32_e32 v75, 0x80000000, v58
	v_mov_b32_e32 v74, v59
	v_pk_add_f32 v[58:59], v[72:73], v[66:67]
	v_pk_add_f32 v[66:67], v[72:73], v[66:67] neg_lo:[0,1] neg_hi:[0,1]
	v_pk_mul_f32 v[72:73], v[84:85], s[14:15] op_sel_hi:[1,0]
	v_pk_add_f32 v[108:109], v[2:3], v[74:75]
	v_pk_add_f32 v[2:3], v[2:3], v[74:75] neg_lo:[0,1] neg_hi:[0,1]
	v_pk_fma_f32 v[74:75], v[84:85], s[22:23], v[72:73] op_sel:[0,0,1] op_sel_hi:[1,0,0]
	v_pk_fma_f32 v[72:73], v[84:85], s[22:23], v[72:73] op_sel:[0,0,1] op_sel_hi:[1,0,0] neg_lo:[0,0,1] neg_hi:[0,0,1]
	s_nop 0
	v_mov_b32_e32 v75, v73
	v_pk_mul_f32 v[72:73], v[6:7], s[24:25] op_sel_hi:[1,0]
	s_nop 0
	v_pk_fma_f32 v[84:85], v[6:7], s[24:25], v[72:73] op_sel:[0,0,1] op_sel_hi:[1,0,0]
	v_pk_fma_f32 v[6:7], v[6:7], s[24:25], v[72:73] op_sel_hi:[1,0,0] neg_lo:[0,0,1] neg_hi:[0,0,1]
	v_pk_mul_f32 v[72:73], v[56:57], s[22:23] op_sel_hi:[1,0]
	v_mov_b32_e32 v85, v7
	v_pk_fma_f32 v[110:111], v[56:57], s[14:15], v[72:73] op_sel:[0,0,1] op_sel_hi:[1,0,0]
	v_pk_fma_f32 v[56:57], v[56:57], s[14:15], v[72:73] op_sel:[0,0,1] op_sel_hi:[1,0,0] neg_lo:[0,0,1] neg_hi:[0,0,1]
	s_nop 0
	v_mov_b32_e32 v111, v57
	v_pk_mul_f32 v[56:57], v[76:77], s[24:25] op_sel_hi:[1,0]
	s_nop 0
	v_pk_fma_f32 v[72:73], v[76:77], s[24:25], v[56:57] op_sel:[0,0,1] op_sel_hi:[1,0,0]
	v_pk_fma_f32 v[56:57], v[76:77], s[24:25], v[56:57] op_sel_hi:[1,0,0] neg_lo:[0,0,1] neg_hi:[0,0,1]
	s_nop 0
	v_mov_b32_e32 v73, v57
	v_pk_fma_f32 v[56:57], v[70:71], 0, v[70:71] op_sel:[0,0,1] op_sel_hi:[1,0,0]
	v_pk_fma_f32 v[70:71], v[70:71], 0, v[70:71] op_sel:[0,0,1] op_sel_hi:[1,0,0] neg_lo:[0,0,1] neg_hi:[0,0,1]
	s_nop 0
	v_mov_b32_e32 v57, v71
	v_pk_mul_f32 v[70:71], v[54:55], s[26:27] op_sel_hi:[1,0]
	s_nop 0
	v_pk_fma_f32 v[76:77], v[54:55], s[26:27], v[70:71] op_sel:[0,0,1] op_sel_hi:[1,0,0] neg_lo:[0,0,1] neg_hi:[0,0,1]
	v_pk_fma_f32 v[54:55], v[54:55], s[26:27], v[70:71] op_sel_hi:[1,0,0]
	v_pk_mul_f32 v[70:71], v[108:109], s[22:23] op_sel_hi:[1,0]
	v_mov_b32_e32 v77, v55
	v_pk_fma_f32 v[112:113], v[108:109], s[14:15], v[70:71] op_sel:[0,0,1] op_sel_hi:[1,0,0]
	v_pk_fma_f32 v[70:71], v[108:109], s[14:15], v[70:71] op_sel:[0,0,1] op_sel_hi:[1,0,0] neg_lo:[0,0,1] neg_hi:[0,0,1]
	v_pk_add_f32 v[54:55], v[0:1], v[76:77]
	v_mov_b32_e32 v113, v71
	v_pk_mul_f32 v[70:71], v[66:67], s[26:27] op_sel_hi:[1,0]
	v_pk_add_f32 v[0:1], v[0:1], v[76:77] neg_lo:[0,1] neg_hi:[0,1]
	v_pk_fma_f32 v[108:109], v[66:67], s[26:27], v[70:71] op_sel:[0,0,1] op_sel_hi:[1,0,0] neg_lo:[0,0,1] neg_hi:[0,0,1]
	v_pk_fma_f32 v[66:67], v[66:67], s[26:27], v[70:71] op_sel_hi:[1,0,0]
	s_nop 0
	v_mov_b32_e32 v109, v67
	v_pk_mul_f32 v[66:67], v[2:3], s[30:31] op_sel:[1,0]
	v_pk_add_f32 v[6:7], v[84:85], v[108:109]
	v_pk_fma_f32 v[2:3], v[2:3], s[28:29], v[66:67] op_sel_hi:[0,1,1]
	v_pk_add_f32 v[66:67], v[64:65], v[60:61]
	v_pk_add_f32 v[60:61], v[64:65], v[60:61] neg_lo:[0,1] neg_hi:[0,1]
	v_pk_add_f32 v[64:65], v[62:63], v[58:59]
	v_pk_add_f32 v[58:59], v[62:63], v[58:59] neg_lo:[0,1] neg_hi:[0,1]
	s_nop 0
	v_xor_b32_e32 v63, 0x80000000, v58
	v_mov_b32_e32 v62, v59
	v_pk_add_f32 v[58:59], v[66:67], v[64:65]
	v_pk_add_f32 v[70:71], v[60:61], v[62:63]
	v_pk_add_f32 v[64:65], v[66:67], v[64:65] neg_lo:[0,1] neg_hi:[0,1]
	v_pk_add_f32 v[60:61], v[60:61], v[62:63] neg_lo:[0,1] neg_hi:[0,1]
	v_pk_add_f32 v[62:63], v[86:87], v[72:73]
	v_pk_add_f32 v[66:67], v[86:87], v[72:73] neg_lo:[0,1] neg_hi:[0,1]
	v_pk_add_f32 v[72:73], v[74:75], v[112:113]
	v_pk_add_f32 v[74:75], v[74:75], v[112:113] neg_lo:[0,1] neg_hi:[0,1]
	s_nop 0
	v_xor_b32_e32 v87, 0x80000000, v74
	v_mov_b32_e32 v86, v75
	v_pk_add_f32 v[74:75], v[62:63], v[72:73]
	v_pk_add_f32 v[62:63], v[62:63], v[72:73] neg_lo:[0,1] neg_hi:[0,1]
	v_pk_add_f32 v[72:73], v[4:5], v[56:57]
	v_pk_add_f32 v[4:5], v[4:5], v[56:57] neg_lo:[0,1] neg_hi:[0,1]
	v_pk_add_f32 v[56:57], v[84:85], v[108:109] neg_lo:[0,1] neg_hi:[0,1]
	v_pk_add_f32 v[112:113], v[66:67], v[86:87]
	v_xor_b32_e32 v85, 0x80000000, v56
	v_mov_b32_e32 v84, v57
	v_pk_add_f32 v[56:57], v[72:73], v[6:7]
	v_pk_add_f32 v[6:7], v[72:73], v[6:7] neg_lo:[0,1] neg_hi:[0,1]
	v_pk_add_f32 v[72:73], v[110:111], v[2:3]
	v_pk_add_f32 v[2:3], v[110:111], v[2:3] neg_lo:[0,1] neg_hi:[0,1]
	v_pk_add_f32 v[66:67], v[66:67], v[86:87] neg_lo:[0,1] neg_hi:[0,1]
	v_xor_b32_e32 v77, 0x80000000, v2
	v_mov_b32_e32 v76, v3
	v_pk_add_f32 v[2:3], v[54:55], v[72:73]
	v_pk_add_f32 v[54:55], v[54:55], v[72:73] neg_lo:[0,1] neg_hi:[0,1]
	v_lshlrev_b32_e32 v73, 3, v8
	v_ashrrev_i32_e32 v8, 4, v8
	v_add_u32_e32 v72, 0, v91
	v_lshlrev_b32_e32 v8, 3, v8
	v_add3_u32 v8, v72, v73, v8
	v_add_u32_e32 v72, 0x1800, v8
	v_pk_add_f32 v[86:87], v[4:5], v[84:85]
	v_pk_add_f32 v[4:5], v[4:5], v[84:85] neg_lo:[0,1] neg_hi:[0,1]
	v_pk_add_f32 v[84:85], v[0:1], v[76:77]
	v_pk_add_f32 v[0:1], v[0:1], v[76:77] neg_lo:[0,1] neg_hi:[0,1]
	ds_write2_b64 v72, v[58:59], v[74:75] offset0:16 offset1:33
	ds_write2_b64 v72, v[56:57], v[2:3] offset0:50 offset1:67
	ds_write2_b64 v72, v[70:71], v[112:113] offset0:84 offset1:101
	ds_write2_b64 v72, v[86:87], v[84:85] offset0:118 offset1:135
	ds_write2_b64 v72, v[64:65], v[62:63] offset0:152 offset1:169
	ds_write2_b64 v72, v[6:7], v[54:55] offset0:186 offset1:203
	ds_write2_b64 v72, v[60:61], v[66:67] offset0:220 offset1:237
	v_add_u32_e32 v2, 0x1c00, v8
	ds_write2_b64 v2, v[4:5], v[0:1] offset0:126 offset1:143
